# instruction selection: accumulator re-zeroing with 64 v_mov_b64 instead of 127 v_mov_b32 in every GEMM tile loop (23 sites)
# baseline (speedup 1.0000x reference)
; template <class Epi, class Sched>
; __device__ __forceinline__ void gemm_phase(LAS unsigned char* lds, const Gemm g, const Sched& S, const Epi& E, const int wave_) {
;     ...
; #pragma unroll
;     for (int a = 0; a < 2; ++a)
; #pragma unroll
;         for (int b = 0; b < 2; ++b)
; #pragma unroll
;             for (int m = 0; m < 4; ++m)
; #pragma unroll
;                 for (int n = 0; n < 2; ++n) acc[a][b][m][n] = (f32x4){0.f, 0.f, 0.f, 0.f};
;     ...
;         const bool has_next = S.next(ui + 1, nxt);
;         const char* nA = has_next ? (const char*)g.A + nxt.aoff : cA; const char* nB = has_next ? (const char*)g.Bt + nxt.boff : cB;
; #pragma unroll 1
;         for (int t = 0; t < nt; t += 2) {
;             if constexpr (Epi::HOOK) { if (t == 8 || t == 16) { E.hook(acc, cur, t >> 3, wr, wc, fr, fq); PG8_WAIT_V(0); } }
;             const bool last = (t == nt - 2);
;             const char* a1 = cA + (size_t)(t + 1) * kstep;
;             const char* a2 = last ? nA : cA + (size_t)(t + 2) * kstep; const char* b2 = last ? nB : cB + (size_t)(t + 2) * kstep;
;             const char* a3 = a2 + kstep; const char* b3 = b2 + kstep;
;             PG8_LDB(B0, 0, 0); PG8_LDB(B1, 0, 1); PG8_SCHED; PG8_LDA(At, 0, 0); PG8_STAGE(PG8_SA(1, 1), a1 + hstepA, voffA);
;             PG8_WAIT_V(8); PG8_WAIT_L(0); PG8_BAR; PG8_MMA(0, 0, At, B0); PG8_MMA(0, 1, At, B1); PG8_BAR; PG8_SCHED;
;             PG8_LDA(At, 0, 1); PG8_STAGE(PG8_SB(0, 0), b2, voffB); PG8_STAGE(PG8_SB(0, 1), b2 + hstepB, voffB); PG8_STAGE(PG8_SA(0, 0), a2, voffA);
;             PG8_WAIT_V(8); PG8_WAIT_L(0); PG8_BAR; PG8_MMA(1, 0, At, B0); PG8_MMA(1, 1, At, B1); PG8_BAR; PG8_SCHED;
;             PG8_LDB(B0, 1, 0); PG8_LDB(B1, 1, 1); PG8_SCHED; PG8_LDA(At, 1, 0); PG8_STAGE(PG8_SA(0, 1), a2 + hstepA, voffA);
;             PG8_WAIT_V(8); PG8_WAIT_L(0); PG8_BAR; PG8_MMA(0, 0, At, B0); PG8_MMA(0, 1, At, B1); PG8_BAR; PG8_SCHED;
;             PG8_LDA(At, 1, 1); PG8_STAGE(PG8_SB(1, 0), b3, voffB); PG8_STAGE(PG8_SB(1, 1), b3 + hstepB, voffB); PG8_STAGE(PG8_SA(1, 0), a3, voffA);
;             PG8_WAIT_V(8); PG8_WAIT_L(0); PG8_BAR; PG8_MMA(1, 0, At, B0); PG8_MMA(1, 1, At, B1); PG8_BAR; PG8_SCHED;
;         }
;         if (wr == 0) PG8_BAR;
;         E(acc, cur, wr, wc, fr, fq);
;         if (!has_next) break;
; #pragma unroll
;         for (int a = 0; a < 2; ++a)
; #pragma unroll
;             for (int b = 0; b < 2; ++b)
.LBB0_181:
	s_add_u32 s64, s34, s60
	s_addc_u32 s65, s35, s61
	s_add_u32 s66, s30, s62
	v_mov_b32_e32 v123, 0
	s_addc_u32 s67, s31, s63
	s_andn2_b64 vcc, exec, s[48:49]
	v_mov_b64_e32 v[0:1], 0
	v_mov_b64_e32 v[2:3], 0
	v_mov_b64_e32 v[4:5], 0
	v_mov_b64_e32 v[6:7], 0
	v_mov_b64_e32 v[8:9], 0
	v_mov_b64_e32 v[10:11], 0
	v_mov_b64_e32 v[12:13], 0
	v_mov_b64_e32 v[14:15], 0
	v_mov_b64_e32 v[16:17], 0
	v_mov_b64_e32 v[18:19], 0
	v_mov_b64_e32 v[20:21], 0
	v_mov_b64_e32 v[22:23], 0
	v_mov_b64_e32 v[24:25], 0
	v_mov_b64_e32 v[26:27], 0
	v_mov_b64_e32 v[28:29], 0
	v_mov_b64_e32 v[30:31], 0
	v_mov_b64_e32 v[32:33], 0
	v_mov_b64_e32 v[34:35], 0
	v_mov_b64_e32 v[36:37], 0
	v_mov_b64_e32 v[38:39], 0
	v_mov_b64_e32 v[40:41], 0
	v_mov_b64_e32 v[42:43], 0
	v_mov_b64_e32 v[44:45], 0
	v_mov_b64_e32 v[46:47], 0
	v_mov_b64_e32 v[48:49], 0
	v_mov_b64_e32 v[50:51], 0
	v_mov_b64_e32 v[52:53], 0
	v_mov_b64_e32 v[54:55], 0
	v_mov_b64_e32 v[56:57], 0
	v_mov_b64_e32 v[58:59], 0
	v_mov_b64_e32 v[60:61], 0
	v_mov_b64_e32 v[62:63], 0
	v_mov_b64_e32 v[64:65], 0
	v_mov_b64_e32 v[66:67], 0
	v_mov_b64_e32 v[68:69], 0
	v_mov_b64_e32 v[70:71], 0
	v_mov_b64_e32 v[72:73], 0
	v_mov_b64_e32 v[74:75], 0
	v_mov_b64_e32 v[76:77], 0
	v_mov_b64_e32 v[78:79], 0
	v_mov_b64_e32 v[80:81], 0
	v_mov_b64_e32 v[82:83], 0
	v_mov_b64_e32 v[84:85], 0
	v_mov_b64_e32 v[86:87], 0
	v_mov_b64_e32 v[88:89], 0
	v_mov_b64_e32 v[90:91], 0
	v_mov_b64_e32 v[92:93], 0
	v_mov_b64_e32 v[94:95], 0
	v_mov_b64_e32 v[96:97], 0
	v_mov_b64_e32 v[98:99], 0
	v_mov_b64_e32 v[100:101], 0
	v_mov_b64_e32 v[102:103], 0
	v_mov_b64_e32 v[104:105], 0
	v_mov_b64_e32 v[106:107], 0
	v_mov_b64_e32 v[108:109], 0
	v_mov_b64_e32 v[110:111], 0
	v_mov_b64_e32 v[112:113], 0
	v_mov_b64_e32 v[114:115], 0
	v_mov_b64_e32 v[116:117], 0
	v_mov_b64_e32 v[118:119], 0
	v_mov_b64_e32 v[120:121], 0
	v_mov_b64_e32 v[122:123], 0
	v_mov_b64_e32 v[124:125], 0
	v_mov_b64_e32 v[126:127], 0
	s_cbranch_vccnz .LBB0_184
	s_and_b64 s[70:71], s[4:5], exec
	s_cselect_b32 s7, s65, s69
	s_cselect_b32 s38, s64, s68
	s_cselect_b32 s57, s67, s9
	s_cselect_b32 s59, s66, s8
	s_add_u32 s72, s8, 0x100
	s_addc_u32 s73, s9, 0
	s_add_u32 s8, s68, 0x40080
	v_mov_b32_e32 v0, 0
	s_addc_u32 s9, s69, 0
	s_mov_b32 s68, 0
	v_mov_b64_e32 v[0:1], 0
	v_mov_b64_e32 v[2:3], 0
	v_mov_b64_e32 v[4:5], 0
	v_mov_b64_e32 v[6:7], 0
	v_mov_b64_e32 v[8:9], 0
	v_mov_b64_e32 v[10:11], 0
	v_mov_b64_e32 v[12:13], 0
	v_mov_b64_e32 v[14:15], 0
	v_mov_b64_e32 v[16:17], 0
	v_mov_b64_e32 v[18:19], 0
	v_mov_b64_e32 v[20:21], 0
	v_mov_b64_e32 v[22:23], 0
	v_mov_b64_e32 v[24:25], 0
	v_mov_b64_e32 v[26:27], 0
	v_mov_b64_e32 v[28:29], 0
	v_mov_b64_e32 v[30:31], 0
	v_mov_b64_e32 v[32:33], 0
	v_mov_b64_e32 v[34:35], 0
	v_mov_b64_e32 v[36:37], 0
	v_mov_b64_e32 v[38:39], 0
	v_mov_b64_e32 v[40:41], 0
	v_mov_b64_e32 v[42:43], 0
	v_mov_b64_e32 v[44:45], 0
	v_mov_b64_e32 v[46:47], 0
	v_mov_b64_e32 v[48:49], 0
	v_mov_b64_e32 v[50:51], 0
	v_mov_b64_e32 v[52:53], 0
	v_mov_b64_e32 v[54:55], 0
	v_mov_b64_e32 v[56:57], 0
	v_mov_b64_e32 v[58:59], 0
	v_mov_b64_e32 v[60:61], 0
	v_mov_b64_e32 v[62:63], 0
	v_mov_b64_e32 v[64:65], 0
	v_mov_b64_e32 v[66:67], 0
	v_mov_b64_e32 v[68:69], 0
	v_mov_b64_e32 v[70:71], 0
	v_mov_b64_e32 v[72:73], 0
	v_mov_b64_e32 v[74:75], 0
	v_mov_b64_e32 v[76:77], 0
	v_mov_b64_e32 v[78:79], 0
	v_mov_b64_e32 v[80:81], 0
	v_mov_b64_e32 v[82:83], 0
	v_mov_b64_e32 v[84:85], 0
	v_mov_b64_e32 v[86:87], 0
	v_mov_b64_e32 v[88:89], 0
	v_mov_b64_e32 v[90:91], 0
	v_mov_b64_e32 v[92:93], 0
	v_mov_b64_e32 v[94:95], 0
	v_mov_b64_e32 v[96:97], 0
	v_mov_b64_e32 v[98:99], 0
	v_mov_b64_e32 v[100:101], 0
	v_mov_b64_e32 v[102:103], 0
	v_mov_b64_e32 v[104:105], 0
	v_mov_b64_e32 v[106:107], 0
	v_mov_b64_e32 v[108:109], 0
	v_mov_b64_e32 v[110:111], 0
	v_mov_b64_e32 v[112:113], 0
	v_mov_b64_e32 v[114:115], 0
	v_mov_b64_e32 v[116:117], 0
	v_mov_b64_e32 v[118:119], 0
	v_mov_b64_e32 v[120:121], 0
	v_mov_b64_e32 v[122:123], 0
	v_mov_b64_e32 v[124:125], 0
	v_mov_b64_e32 v[126:127], 0

; template <class Epi, class Sched>
; __device__ __forceinline__ void gemm_phase(LAS unsigned char* lds, const Gemm g, const Sched& S, const Epi& E, const int wave_) {
;     ...
; #pragma unroll
;     for (int a = 0; a < 2; ++a)
; #pragma unroll
;         for (int b = 0; b < 2; ++b)
; #pragma unroll
;             for (int m = 0; m < 4; ++m)
; #pragma unroll
;                 for (int n = 0; n < 2; ++n) acc[a][b][m][n] = (f32x4){0.f, 0.f, 0.f, 0.f};
;     ...
;         const bool has_next = S.next(ui + 1, nxt);
;         const char* nA = has_next ? (const char*)g.A + nxt.aoff : cA; const char* nB = has_next ? (const char*)g.Bt + nxt.boff : cB;
; #pragma unroll 1
;         for (int t = 0; t < nt; t += 2) {
;             if constexpr (Epi::HOOK) { if (t == 8 || t == 16) { E.hook(acc, cur, t >> 3, wr, wc, fr, fq); PG8_WAIT_V(0); } }
;             const bool last = (t == nt - 2);
;             const char* a1 = cA + (size_t)(t + 1) * kstep;
;             const char* a2 = last ? nA : cA + (size_t)(t + 2) * kstep; const char* b2 = last ? nB : cB + (size_t)(t + 2) * kstep;
;             const char* a3 = a2 + kstep; const char* b3 = b2 + kstep;
;             PG8_LDB(B0, 0, 0); PG8_LDB(B1, 0, 1); PG8_SCHED; PG8_LDA(At, 0, 0); PG8_STAGE(PG8_SA(1, 1), a1 + hstepA, voffA);
;             PG8_WAIT_V(8); PG8_WAIT_L(0); PG8_BAR; PG8_MMA(0, 0, At, B0); PG8_MMA(0, 1, At, B1); PG8_BAR; PG8_SCHED;
;             PG8_LDA(At, 0, 1); PG8_STAGE(PG8_SB(0, 0), b2, voffB); PG8_STAGE(PG8_SB(0, 1), b2 + hstepB, voffB); PG8_STAGE(PG8_SA(0, 0), a2, voffA);
;             PG8_WAIT_V(8); PG8_WAIT_L(0); PG8_BAR; PG8_MMA(1, 0, At, B0); PG8_MMA(1, 1, At, B1); PG8_BAR; PG8_SCHED;
;             PG8_LDB(B0, 1, 0); PG8_LDB(B1, 1, 1); PG8_SCHED; PG8_LDA(At, 1, 0); PG8_STAGE(PG8_SA(0, 1), a2 + hstepA, voffA);
;             PG8_WAIT_V(8); PG8_WAIT_L(0); PG8_BAR; PG8_MMA(0, 0, At, B0); PG8_MMA(0, 1, At, B1); PG8_BAR; PG8_SCHED;
;             PG8_LDA(At, 1, 1); PG8_STAGE(PG8_SB(1, 0), b3, voffB); PG8_STAGE(PG8_SB(1, 1), b3 + hstepB, voffB); PG8_STAGE(PG8_SA(1, 0), a3, voffA);
;             PG8_WAIT_V(8); PG8_WAIT_L(0); PG8_BAR; PG8_MMA(1, 0, At, B0); PG8_MMA(1, 1, At, B1); PG8_BAR; PG8_SCHED;
;         }
;         if (wr == 0) PG8_BAR;
;         E(acc, cur, wr, wc, fr, fq);
;         if (!has_next) break;
; #pragma unroll
;         for (int a = 0; a < 2; ++a)
; #pragma unroll
;             for (int b = 0; b < 2; ++b)
.LBB0_522:
	s_add_u32 s50, s10, s46
	s_addc_u32 s51, s11, s47
	s_add_u32 s52, s29, s48
	v_mov_b32_e32 v123, 0
	s_addc_u32 s53, s60, s49
	s_andn2_b64 vcc, exec, s[36:37]
	v_mov_b64_e32 v[0:1], 0
	v_mov_b64_e32 v[2:3], 0
	v_mov_b64_e32 v[4:5], 0
	v_mov_b64_e32 v[6:7], 0
	v_mov_b64_e32 v[8:9], 0
	v_mov_b64_e32 v[10:11], 0
	v_mov_b64_e32 v[12:13], 0
	v_mov_b64_e32 v[14:15], 0
	v_mov_b64_e32 v[16:17], 0
	v_mov_b64_e32 v[18:19], 0
	v_mov_b64_e32 v[20:21], 0
	v_mov_b64_e32 v[22:23], 0
	v_mov_b64_e32 v[24:25], 0
	v_mov_b64_e32 v[26:27], 0
	v_mov_b64_e32 v[28:29], 0
	v_mov_b64_e32 v[30:31], 0
	v_mov_b64_e32 v[32:33], 0
	v_mov_b64_e32 v[34:35], 0
	v_mov_b64_e32 v[36:37], 0
	v_mov_b64_e32 v[38:39], 0
	v_mov_b64_e32 v[40:41], 0
	v_mov_b64_e32 v[42:43], 0
	v_mov_b64_e32 v[44:45], 0
	v_mov_b64_e32 v[46:47], 0
	v_mov_b64_e32 v[48:49], 0
	v_mov_b64_e32 v[50:51], 0
	v_mov_b64_e32 v[52:53], 0
	v_mov_b64_e32 v[54:55], 0
	v_mov_b64_e32 v[56:57], 0
	v_mov_b64_e32 v[58:59], 0
	v_mov_b64_e32 v[60:61], 0
	v_mov_b64_e32 v[62:63], 0
	v_mov_b64_e32 v[64:65], 0
	v_mov_b64_e32 v[66:67], 0
	v_mov_b64_e32 v[68:69], 0
	v_mov_b64_e32 v[70:71], 0
	v_mov_b64_e32 v[72:73], 0
	v_mov_b64_e32 v[74:75], 0
	v_mov_b64_e32 v[76:77], 0
	v_mov_b64_e32 v[78:79], 0
	v_mov_b64_e32 v[80:81], 0
	v_mov_b64_e32 v[82:83], 0
	v_mov_b64_e32 v[84:85], 0
	v_mov_b64_e32 v[86:87], 0
	v_mov_b64_e32 v[88:89], 0
	v_mov_b64_e32 v[90:91], 0
	v_mov_b64_e32 v[92:93], 0
	v_mov_b64_e32 v[94:95], 0
	v_mov_b64_e32 v[96:97], 0
	v_mov_b64_e32 v[98:99], 0
	v_mov_b64_e32 v[100:101], 0
	v_mov_b64_e32 v[102:103], 0
	v_mov_b64_e32 v[104:105], 0
	v_mov_b64_e32 v[106:107], 0
	v_mov_b64_e32 v[108:109], 0
	v_mov_b64_e32 v[110:111], 0
	v_mov_b64_e32 v[112:113], 0
	v_mov_b64_e32 v[114:115], 0
	v_mov_b64_e32 v[116:117], 0
	v_mov_b64_e32 v[118:119], 0
	v_mov_b64_e32 v[120:121], 0
	v_mov_b64_e32 v[122:123], 0
	v_mov_b64_e32 v[124:125], 0
	v_mov_b64_e32 v[126:127], 0
	s_cbranch_vccnz .LBB0_525
	s_and_b64 s[58:59], s[44:45], exec
	s_cselect_b32 s43, s51, s57
	s_cselect_b32 s73, s50, s56
	s_cselect_b32 s74, s53, s55
	s_cselect_b32 s75, s52, s54
	s_add_u32 s76, s54, 0x100
	s_addc_u32 s77, s55, 0
	s_add_u32 s54, s56, 0x40080
	v_mov_b32_e32 v0, 0
	s_addc_u32 s55, s57, 0
	s_mov_b32 s56, 0
	v_mov_b64_e32 v[0:1], 0
	v_mov_b64_e32 v[2:3], 0
	v_mov_b64_e32 v[4:5], 0
	v_mov_b64_e32 v[6:7], 0
	v_mov_b64_e32 v[8:9], 0
	v_mov_b64_e32 v[10:11], 0
	v_mov_b64_e32 v[12:13], 0
	v_mov_b64_e32 v[14:15], 0
	v_mov_b64_e32 v[16:17], 0
	v_mov_b64_e32 v[18:19], 0
	v_mov_b64_e32 v[20:21], 0
	v_mov_b64_e32 v[22:23], 0
	v_mov_b64_e32 v[24:25], 0
	v_mov_b64_e32 v[26:27], 0
	v_mov_b64_e32 v[28:29], 0
	v_mov_b64_e32 v[30:31], 0
	v_mov_b64_e32 v[32:33], 0
	v_mov_b64_e32 v[34:35], 0
	v_mov_b64_e32 v[36:37], 0
	v_mov_b64_e32 v[38:39], 0
	v_mov_b64_e32 v[40:41], 0
	v_mov_b64_e32 v[42:43], 0
	v_mov_b64_e32 v[44:45], 0
	v_mov_b64_e32 v[46:47], 0
	v_mov_b64_e32 v[48:49], 0
	v_mov_b64_e32 v[50:51], 0
	v_mov_b64_e32 v[52:53], 0
	v_mov_b64_e32 v[54:55], 0
	v_mov_b64_e32 v[56:57], 0
	v_mov_b64_e32 v[58:59], 0
	v_mov_b64_e32 v[60:61], 0
	v_mov_b64_e32 v[62:63], 0
	v_mov_b64_e32 v[64:65], 0
	v_mov_b64_e32 v[66:67], 0
	v_mov_b64_e32 v[68:69], 0
	v_mov_b64_e32 v[70:71], 0
	v_mov_b64_e32 v[72:73], 0
	v_mov_b64_e32 v[74:75], 0
	v_mov_b64_e32 v[76:77], 0
	v_mov_b64_e32 v[78:79], 0
	v_mov_b64_e32 v[80:81], 0
	v_mov_b64_e32 v[82:83], 0
	v_mov_b64_e32 v[84:85], 0
	v_mov_b64_e32 v[86:87], 0
	v_mov_b64_e32 v[88:89], 0
	v_mov_b64_e32 v[90:91], 0
	v_mov_b64_e32 v[92:93], 0
	v_mov_b64_e32 v[94:95], 0
	v_mov_b64_e32 v[96:97], 0
	v_mov_b64_e32 v[98:99], 0
	v_mov_b64_e32 v[100:101], 0
	v_mov_b64_e32 v[102:103], 0
	v_mov_b64_e32 v[104:105], 0
	v_mov_b64_e32 v[106:107], 0
	v_mov_b64_e32 v[108:109], 0
	v_mov_b64_e32 v[110:111], 0
	v_mov_b64_e32 v[112:113], 0
	v_mov_b64_e32 v[114:115], 0
	v_mov_b64_e32 v[116:117], 0
	v_mov_b64_e32 v[118:119], 0
	v_mov_b64_e32 v[120:121], 0
	v_mov_b64_e32 v[122:123], 0
	v_mov_b64_e32 v[124:125], 0
	v_mov_b64_e32 v[126:127], 0

; template <class Epi, class Sched>
; __device__ __forceinline__ void gemm_phase(LAS unsigned char* lds, const Gemm g, const Sched& S, const Epi& E, const int wave_) {
;     ...
; #pragma unroll
;     for (int a = 0; a < 2; ++a)
; #pragma unroll
;         for (int b = 0; b < 2; ++b)
; #pragma unroll
;             for (int m = 0; m < 4; ++m)
; #pragma unroll
;                 for (int n = 0; n < 2; ++n) acc[a][b][m][n] = (f32x4){0.f, 0.f, 0.f, 0.f};
;     ...
;         const bool has_next = S.next(ui + 1, nxt);
;         const char* nA = has_next ? (const char*)g.A + nxt.aoff : cA; const char* nB = has_next ? (const char*)g.Bt + nxt.boff : cB;
; #pragma unroll 1
;         for (int t = 0; t < nt; t += 2) {
;             if constexpr (Epi::HOOK) { if (t == 8 || t == 16) { E.hook(acc, cur, t >> 3, wr, wc, fr, fq); PG8_WAIT_V(0); } }
;             const bool last = (t == nt - 2);
;             const char* a1 = cA + (size_t)(t + 1) * kstep;
;             const char* a2 = last ? nA : cA + (size_t)(t + 2) * kstep; const char* b2 = last ? nB : cB + (size_t)(t + 2) * kstep;
;             const char* a3 = a2 + kstep; const char* b3 = b2 + kstep;
;             PG8_LDB(B0, 0, 0); PG8_LDB(B1, 0, 1); PG8_SCHED; PG8_LDA(At, 0, 0); PG8_STAGE(PG8_SA(1, 1), a1 + hstepA, voffA);
;             PG8_WAIT_V(8); PG8_WAIT_L(0); PG8_BAR; PG8_MMA(0, 0, At, B0); PG8_MMA(0, 1, At, B1); PG8_BAR; PG8_SCHED;
;             PG8_LDA(At, 0, 1); PG8_STAGE(PG8_SB(0, 0), b2, voffB); PG8_STAGE(PG8_SB(0, 1), b2 + hstepB, voffB); PG8_STAGE(PG8_SA(0, 0), a2, voffA);
;             PG8_WAIT_V(8); PG8_WAIT_L(0); PG8_BAR; PG8_MMA(1, 0, At, B0); PG8_MMA(1, 1, At, B1); PG8_BAR; PG8_SCHED;
;             PG8_LDB(B0, 1, 0); PG8_LDB(B1, 1, 1); PG8_SCHED; PG8_LDA(At, 1, 0); PG8_STAGE(PG8_SA(0, 1), a2 + hstepA, voffA);
;             PG8_WAIT_V(8); PG8_WAIT_L(0); PG8_BAR; PG8_MMA(0, 0, At, B0); PG8_MMA(0, 1, At, B1); PG8_BAR; PG8_SCHED;
;             PG8_LDA(At, 1, 1); PG8_STAGE(PG8_SB(1, 0), b3, voffB); PG8_STAGE(PG8_SB(1, 1), b3 + hstepB, voffB); PG8_STAGE(PG8_SA(1, 0), a3, voffA);
;             PG8_WAIT_V(8); PG8_WAIT_L(0); PG8_BAR; PG8_MMA(1, 0, At, B0); PG8_MMA(1, 1, At, B1); PG8_BAR; PG8_SCHED;
;         }
;         if (wr == 0) PG8_BAR;
;         E(acc, cur, wr, wc, fr, fq);
;         if (!has_next) break;
; #pragma unroll
;         for (int a = 0; a < 2; ++a)
; #pragma unroll
;             for (int b = 0; b < 2; ++b)
.LBB0_547:
	s_add_u32 s50, s60, s46
	s_addc_u32 s51, s61, s47
	s_add_u32 s52, s10, s48
	v_mov_b32_e32 v123, 0
	s_addc_u32 s53, s11, s49
	s_andn2_b64 vcc, exec, s[8:9]
	v_mov_b64_e32 v[0:1], 0
	v_mov_b64_e32 v[2:3], 0
	v_mov_b64_e32 v[4:5], 0
	v_mov_b64_e32 v[6:7], 0
	v_mov_b64_e32 v[8:9], 0
	v_mov_b64_e32 v[10:11], 0
	v_mov_b64_e32 v[12:13], 0
	v_mov_b64_e32 v[14:15], 0
	v_mov_b64_e32 v[16:17], 0
	v_mov_b64_e32 v[18:19], 0
	v_mov_b64_e32 v[20:21], 0
	v_mov_b64_e32 v[22:23], 0
	v_mov_b64_e32 v[24:25], 0
	v_mov_b64_e32 v[26:27], 0
	v_mov_b64_e32 v[28:29], 0
	v_mov_b64_e32 v[30:31], 0
	v_mov_b64_e32 v[32:33], 0
	v_mov_b64_e32 v[34:35], 0
	v_mov_b64_e32 v[36:37], 0
	v_mov_b64_e32 v[38:39], 0
	v_mov_b64_e32 v[40:41], 0
	v_mov_b64_e32 v[42:43], 0
	v_mov_b64_e32 v[44:45], 0
	v_mov_b64_e32 v[46:47], 0
	v_mov_b64_e32 v[48:49], 0
	v_mov_b64_e32 v[50:51], 0
	v_mov_b64_e32 v[52:53], 0
	v_mov_b64_e32 v[54:55], 0
	v_mov_b64_e32 v[56:57], 0
	v_mov_b64_e32 v[58:59], 0
	v_mov_b64_e32 v[60:61], 0
	v_mov_b64_e32 v[62:63], 0
	v_mov_b64_e32 v[64:65], 0
	v_mov_b64_e32 v[66:67], 0
	v_mov_b64_e32 v[68:69], 0
	v_mov_b64_e32 v[70:71], 0
	v_mov_b64_e32 v[72:73], 0
	v_mov_b64_e32 v[74:75], 0
	v_mov_b64_e32 v[76:77], 0
	v_mov_b64_e32 v[78:79], 0
	v_mov_b64_e32 v[80:81], 0
	v_mov_b64_e32 v[82:83], 0
	v_mov_b64_e32 v[84:85], 0
	v_mov_b64_e32 v[86:87], 0
	v_mov_b64_e32 v[88:89], 0
	v_mov_b64_e32 v[90:91], 0
	v_mov_b64_e32 v[92:93], 0
	v_mov_b64_e32 v[94:95], 0
	v_mov_b64_e32 v[96:97], 0
	v_mov_b64_e32 v[98:99], 0
	v_mov_b64_e32 v[100:101], 0
	v_mov_b64_e32 v[102:103], 0
	v_mov_b64_e32 v[104:105], 0
	v_mov_b64_e32 v[106:107], 0
	v_mov_b64_e32 v[108:109], 0
	v_mov_b64_e32 v[110:111], 0
	v_mov_b64_e32 v[112:113], 0
	v_mov_b64_e32 v[114:115], 0
	v_mov_b64_e32 v[116:117], 0
	v_mov_b64_e32 v[118:119], 0
	v_mov_b64_e32 v[120:121], 0
	v_mov_b64_e32 v[122:123], 0
	v_mov_b64_e32 v[124:125], 0
	v_mov_b64_e32 v[126:127], 0
	s_cbranch_vccnz .LBB0_550
	s_and_b64 s[58:59], s[40:41], exec
	s_cselect_b32 s43, s51, s57
	s_cselect_b32 s45, s50, s56
	s_cselect_b32 s72, s53, s55
	s_cselect_b32 s73, s52, s54
	s_add_u32 s74, s54, 0x100
	s_addc_u32 s75, s55, 0
	s_add_u32 s54, s56, 0x40080
	v_mov_b32_e32 v0, 0
	s_addc_u32 s55, s57, 0
	s_mov_b32 s56, 0
	v_mov_b64_e32 v[0:1], 0
	v_mov_b64_e32 v[2:3], 0
	v_mov_b64_e32 v[4:5], 0
	v_mov_b64_e32 v[6:7], 0
	v_mov_b64_e32 v[8:9], 0
	v_mov_b64_e32 v[10:11], 0
	v_mov_b64_e32 v[12:13], 0
	v_mov_b64_e32 v[14:15], 0
	v_mov_b64_e32 v[16:17], 0
	v_mov_b64_e32 v[18:19], 0
	v_mov_b64_e32 v[20:21], 0
	v_mov_b64_e32 v[22:23], 0
	v_mov_b64_e32 v[24:25], 0
	v_mov_b64_e32 v[26:27], 0
	v_mov_b64_e32 v[28:29], 0
	v_mov_b64_e32 v[30:31], 0
	v_mov_b64_e32 v[32:33], 0
	v_mov_b64_e32 v[34:35], 0
	v_mov_b64_e32 v[36:37], 0
	v_mov_b64_e32 v[38:39], 0
	v_mov_b64_e32 v[40:41], 0
	v_mov_b64_e32 v[42:43], 0
	v_mov_b64_e32 v[44:45], 0
	v_mov_b64_e32 v[46:47], 0
	v_mov_b64_e32 v[48:49], 0
	v_mov_b64_e32 v[50:51], 0
	v_mov_b64_e32 v[52:53], 0
	v_mov_b64_e32 v[54:55], 0
	v_mov_b64_e32 v[56:57], 0
	v_mov_b64_e32 v[58:59], 0
	v_mov_b64_e32 v[60:61], 0
	v_mov_b64_e32 v[62:63], 0
	v_mov_b64_e32 v[64:65], 0
	v_mov_b64_e32 v[66:67], 0
	v_mov_b64_e32 v[68:69], 0
	v_mov_b64_e32 v[70:71], 0
	v_mov_b64_e32 v[72:73], 0
	v_mov_b64_e32 v[74:75], 0
	v_mov_b64_e32 v[76:77], 0
	v_mov_b64_e32 v[78:79], 0
	v_mov_b64_e32 v[80:81], 0
	v_mov_b64_e32 v[82:83], 0
	v_mov_b64_e32 v[84:85], 0
	v_mov_b64_e32 v[86:87], 0
	v_mov_b64_e32 v[88:89], 0
	v_mov_b64_e32 v[90:91], 0
	v_mov_b64_e32 v[92:93], 0
	v_mov_b64_e32 v[94:95], 0
	v_mov_b64_e32 v[96:97], 0
	v_mov_b64_e32 v[98:99], 0
	v_mov_b64_e32 v[100:101], 0
	v_mov_b64_e32 v[102:103], 0
	v_mov_b64_e32 v[104:105], 0
	v_mov_b64_e32 v[106:107], 0
	v_mov_b64_e32 v[108:109], 0
	v_mov_b64_e32 v[110:111], 0
	v_mov_b64_e32 v[112:113], 0
	v_mov_b64_e32 v[114:115], 0
	v_mov_b64_e32 v[116:117], 0
	v_mov_b64_e32 v[118:119], 0
	v_mov_b64_e32 v[120:121], 0
	v_mov_b64_e32 v[122:123], 0
	v_mov_b64_e32 v[124:125], 0
	v_mov_b64_e32 v[126:127], 0

; template <class Epi, class Sched>
; __device__ __forceinline__ void gemm_phase(LAS unsigned char* lds, const Gemm g, const Sched& S, const Epi& E, const int wave_) {
;     ...
; #pragma unroll
;     for (int a = 0; a < 2; ++a)
; #pragma unroll
;         for (int b = 0; b < 2; ++b)
; #pragma unroll
;             for (int m = 0; m < 4; ++m)
; #pragma unroll
;                 for (int n = 0; n < 2; ++n) acc[a][b][m][n] = (f32x4){0.f, 0.f, 0.f, 0.f};
;     ...
;         const bool has_next = S.next(ui + 1, nxt);
;         const char* nA = has_next ? (const char*)g.A + nxt.aoff : cA; const char* nB = has_next ? (const char*)g.Bt + nxt.boff : cB;
; #pragma unroll 1
;         for (int t = 0; t < nt; t += 2) {
;             if constexpr (Epi::HOOK) { if (t == 8 || t == 16) { E.hook(acc, cur, t >> 3, wr, wc, fr, fq); PG8_WAIT_V(0); } }
;             const bool last = (t == nt - 2);
;             const char* a1 = cA + (size_t)(t + 1) * kstep;
;             const char* a2 = last ? nA : cA + (size_t)(t + 2) * kstep; const char* b2 = last ? nB : cB + (size_t)(t + 2) * kstep;
;             const char* a3 = a2 + kstep; const char* b3 = b2 + kstep;
;             PG8_LDB(B0, 0, 0); PG8_LDB(B1, 0, 1); PG8_SCHED; PG8_LDA(At, 0, 0); PG8_STAGE(PG8_SA(1, 1), a1 + hstepA, voffA);
;             PG8_WAIT_V(8); PG8_WAIT_L(0); PG8_BAR; PG8_MMA(0, 0, At, B0); PG8_MMA(0, 1, At, B1); PG8_BAR; PG8_SCHED;
;             PG8_LDA(At, 0, 1); PG8_STAGE(PG8_SB(0, 0), b2, voffB); PG8_STAGE(PG8_SB(0, 1), b2 + hstepB, voffB); PG8_STAGE(PG8_SA(0, 0), a2, voffA);
;             PG8_WAIT_V(8); PG8_WAIT_L(0); PG8_BAR; PG8_MMA(1, 0, At, B0); PG8_MMA(1, 1, At, B1); PG8_BAR; PG8_SCHED;
;             PG8_LDB(B0, 1, 0); PG8_LDB(B1, 1, 1); PG8_SCHED; PG8_LDA(At, 1, 0); PG8_STAGE(PG8_SA(0, 1), a2 + hstepA, voffA);
;             PG8_WAIT_V(8); PG8_WAIT_L(0); PG8_BAR; PG8_MMA(0, 0, At, B0); PG8_MMA(0, 1, At, B1); PG8_BAR; PG8_SCHED;
;             PG8_LDA(At, 1, 1); PG8_STAGE(PG8_SB(1, 0), b3, voffB); PG8_STAGE(PG8_SB(1, 1), b3 + hstepB, voffB); PG8_STAGE(PG8_SA(1, 0), a3, voffA);
;             PG8_WAIT_V(8); PG8_WAIT_L(0); PG8_BAR; PG8_MMA(1, 0, At, B0); PG8_MMA(1, 1, At, B1); PG8_BAR; PG8_SCHED;
;         }
;         if (wr == 0) PG8_BAR;
;         E(acc, cur, wr, wc, fr, fq);
;         if (!has_next) break;
; #pragma unroll
;         for (int a = 0; a < 2; ++a)
; #pragma unroll
;             for (int b = 0; b < 2; ++b)
.LBB0_615:
	s_add_u32 s42, s10, s40
	s_addc_u32 s43, s11, s41
	s_add_u32 s44, s24, s30
	v_mov_b32_e32 v127, 0
	s_addc_u32 s45, s25, s31
	s_and_b64 vcc, exec, s[4:5]
	v_mov_b64_e32 v[0:1], 0
	v_mov_b64_e32 v[2:3], 0
	v_mov_b64_e32 v[4:5], 0
	v_mov_b64_e32 v[6:7], 0
	v_mov_b64_e32 v[8:9], 0
	v_mov_b64_e32 v[10:11], 0
	v_mov_b64_e32 v[12:13], 0
	v_mov_b64_e32 v[14:15], 0
	v_mov_b64_e32 v[16:17], 0
	v_mov_b64_e32 v[18:19], 0
	v_mov_b64_e32 v[20:21], 0
	v_mov_b64_e32 v[22:23], 0
	v_mov_b64_e32 v[24:25], 0
	v_mov_b64_e32 v[26:27], 0
	v_mov_b64_e32 v[28:29], 0
	v_mov_b64_e32 v[30:31], 0
	v_mov_b64_e32 v[32:33], 0
	v_mov_b64_e32 v[34:35], 0
	v_mov_b64_e32 v[36:37], 0
	v_mov_b64_e32 v[38:39], 0
	v_mov_b64_e32 v[40:41], 0
	v_mov_b64_e32 v[42:43], 0
	v_mov_b64_e32 v[44:45], 0
	v_mov_b64_e32 v[46:47], 0
	v_mov_b64_e32 v[48:49], 0
	v_mov_b64_e32 v[50:51], 0
	v_mov_b64_e32 v[52:53], 0
	v_mov_b64_e32 v[54:55], 0
	v_mov_b64_e32 v[56:57], 0
	v_mov_b64_e32 v[58:59], 0
	v_mov_b64_e32 v[60:61], 0
	v_mov_b64_e32 v[62:63], 0
	v_mov_b64_e32 v[64:65], 0
	v_mov_b64_e32 v[66:67], 0
	v_mov_b64_e32 v[68:69], 0
	v_mov_b64_e32 v[70:71], 0
	v_mov_b64_e32 v[72:73], 0
	v_mov_b64_e32 v[74:75], 0
	v_mov_b64_e32 v[76:77], 0
	v_mov_b64_e32 v[78:79], 0
	v_mov_b64_e32 v[80:81], 0
	v_mov_b64_e32 v[82:83], 0
	v_mov_b64_e32 v[84:85], 0
	v_mov_b64_e32 v[86:87], 0
	v_mov_b64_e32 v[88:89], 0
	v_mov_b64_e32 v[90:91], 0
	v_mov_b64_e32 v[92:93], 0
	v_mov_b64_e32 v[94:95], 0
	v_mov_b64_e32 v[96:97], 0
	v_mov_b64_e32 v[98:99], 0
	v_mov_b64_e32 v[100:101], 0
	v_mov_b64_e32 v[102:103], 0
	v_mov_b64_e32 v[104:105], 0
	v_mov_b64_e32 v[106:107], 0
	v_mov_b64_e32 v[108:109], 0
	v_mov_b64_e32 v[110:111], 0
	v_mov_b64_e32 v[112:113], 0
	v_mov_b64_e32 v[114:115], 0
	v_mov_b64_e32 v[116:117], 0
	v_mov_b64_e32 v[118:119], 0
	v_mov_b64_e32 v[120:121], 0
	v_mov_b64_e32 v[122:123], 0
	v_mov_b64_e32 v[124:125], 0
	v_mov_b64_e32 v[126:127], 0
	s_cbranch_vccnz .LBB0_618
	s_and_b64 s[50:51], s[6:7], exec
	s_cselect_b32 s66, s43, s49
	s_cselect_b32 s67, s42, s48
	s_cselect_b32 s68, s45, s47
	s_cselect_b32 s69, s44, s46
	s_add_u32 s70, s46, 0x100
	s_addc_u32 s71, s47, 0
	s_add_u32 s46, s48, 0x20080
	v_mov_b32_e32 v0, 0
	s_addc_u32 s47, s49, 0
	s_mov_b32 s48, 0
	v_mov_b64_e32 v[0:1], 0
	v_mov_b64_e32 v[2:3], 0
	v_mov_b64_e32 v[4:5], 0
	v_mov_b64_e32 v[6:7], 0
	v_mov_b64_e32 v[8:9], 0
	v_mov_b64_e32 v[10:11], 0
	v_mov_b64_e32 v[12:13], 0
	v_mov_b64_e32 v[14:15], 0
	v_mov_b64_e32 v[16:17], 0
	v_mov_b64_e32 v[18:19], 0
	v_mov_b64_e32 v[20:21], 0
	v_mov_b64_e32 v[22:23], 0
	v_mov_b64_e32 v[24:25], 0
	v_mov_b64_e32 v[26:27], 0
	v_mov_b64_e32 v[28:29], 0
	v_mov_b64_e32 v[30:31], 0
	v_mov_b64_e32 v[32:33], 0
	v_mov_b64_e32 v[34:35], 0
	v_mov_b64_e32 v[36:37], 0
	v_mov_b64_e32 v[38:39], 0
	v_mov_b64_e32 v[40:41], 0
	v_mov_b64_e32 v[42:43], 0
	v_mov_b64_e32 v[44:45], 0
	v_mov_b64_e32 v[46:47], 0
	v_mov_b64_e32 v[48:49], 0
	v_mov_b64_e32 v[50:51], 0
	v_mov_b64_e32 v[52:53], 0
	v_mov_b64_e32 v[54:55], 0
	v_mov_b64_e32 v[56:57], 0
	v_mov_b64_e32 v[58:59], 0
	v_mov_b64_e32 v[60:61], 0
	v_mov_b64_e32 v[62:63], 0
	v_mov_b64_e32 v[64:65], 0
	v_mov_b64_e32 v[66:67], 0
	v_mov_b64_e32 v[68:69], 0
	v_mov_b64_e32 v[70:71], 0
	v_mov_b64_e32 v[72:73], 0
	v_mov_b64_e32 v[74:75], 0
	v_mov_b64_e32 v[76:77], 0
	v_mov_b64_e32 v[78:79], 0
	v_mov_b64_e32 v[80:81], 0
	v_mov_b64_e32 v[82:83], 0
	v_mov_b64_e32 v[84:85], 0
	v_mov_b64_e32 v[86:87], 0
	v_mov_b64_e32 v[88:89], 0
	v_mov_b64_e32 v[90:91], 0
	v_mov_b64_e32 v[92:93], 0
	v_mov_b64_e32 v[94:95], 0
	v_mov_b64_e32 v[96:97], 0
	v_mov_b64_e32 v[98:99], 0
	v_mov_b64_e32 v[100:101], 0
	v_mov_b64_e32 v[102:103], 0
	v_mov_b64_e32 v[104:105], 0
	v_mov_b64_e32 v[106:107], 0
	v_mov_b64_e32 v[108:109], 0
	v_mov_b64_e32 v[110:111], 0
	v_mov_b64_e32 v[112:113], 0
	v_mov_b64_e32 v[114:115], 0
	v_mov_b64_e32 v[116:117], 0
	v_mov_b64_e32 v[118:119], 0
	v_mov_b64_e32 v[120:121], 0
	v_mov_b64_e32 v[122:123], 0
	v_mov_b64_e32 v[124:125], 0
	v_mov_b64_e32 v[126:127], 0

; template <class Epi, class Sched>
; __device__ __forceinline__ void gemm_phase(LAS unsigned char* lds, const Gemm g, const Sched& S, const Epi& E, const int wave_) {
;     ...
; #pragma unroll
;     for (int a = 0; a < 2; ++a)
; #pragma unroll
;         for (int b = 0; b < 2; ++b)
; #pragma unroll
;             for (int m = 0; m < 4; ++m)
; #pragma unroll
;                 for (int n = 0; n < 2; ++n) acc[a][b][m][n] = (f32x4){0.f, 0.f, 0.f, 0.f};
;     ...
;         const bool has_next = S.next(ui + 1, nxt);
;         const char* nA = has_next ? (const char*)g.A + nxt.aoff : cA; const char* nB = has_next ? (const char*)g.Bt + nxt.boff : cB;
; #pragma unroll 1
;         for (int t = 0; t < nt; t += 2) {
;             if constexpr (Epi::HOOK) { if (t == 8 || t == 16) { E.hook(acc, cur, t >> 3, wr, wc, fr, fq); PG8_WAIT_V(0); } }
;             const bool last = (t == nt - 2);
;             const char* a1 = cA + (size_t)(t + 1) * kstep;
;             const char* a2 = last ? nA : cA + (size_t)(t + 2) * kstep; const char* b2 = last ? nB : cB + (size_t)(t + 2) * kstep;
;             const char* a3 = a2 + kstep; const char* b3 = b2 + kstep;
;             PG8_LDB(B0, 0, 0); PG8_LDB(B1, 0, 1); PG8_SCHED; PG8_LDA(At, 0, 0); PG8_STAGE(PG8_SA(1, 1), a1 + hstepA, voffA);
;             PG8_WAIT_V(8); PG8_WAIT_L(0); PG8_BAR; PG8_MMA(0, 0, At, B0); PG8_MMA(0, 1, At, B1); PG8_BAR; PG8_SCHED;
;             PG8_LDA(At, 0, 1); PG8_STAGE(PG8_SB(0, 0), b2, voffB); PG8_STAGE(PG8_SB(0, 1), b2 + hstepB, voffB); PG8_STAGE(PG8_SA(0, 0), a2, voffA);
;             PG8_WAIT_V(8); PG8_WAIT_L(0); PG8_BAR; PG8_MMA(1, 0, At, B0); PG8_MMA(1, 1, At, B1); PG8_BAR; PG8_SCHED;
;             PG8_LDB(B0, 1, 0); PG8_LDB(B1, 1, 1); PG8_SCHED; PG8_LDA(At, 1, 0); PG8_STAGE(PG8_SA(0, 1), a2 + hstepA, voffA);
;             PG8_WAIT_V(8); PG8_WAIT_L(0); PG8_BAR; PG8_MMA(0, 0, At, B0); PG8_MMA(0, 1, At, B1); PG8_BAR; PG8_SCHED;
;             PG8_LDA(At, 1, 1); PG8_STAGE(PG8_SB(1, 0), b3, voffB); PG8_STAGE(PG8_SB(1, 1), b3 + hstepB, voffB); PG8_STAGE(PG8_SA(1, 0), a3, voffA);
;             PG8_WAIT_V(8); PG8_WAIT_L(0); PG8_BAR; PG8_MMA(1, 0, At, B0); PG8_MMA(1, 1, At, B1); PG8_BAR; PG8_SCHED;
;         }
;         if (wr == 0) PG8_BAR;
;         E(acc, cur, wr, wc, fr, fq);
;         if (!has_next) break;
; #pragma unroll
;         for (int a = 0; a < 2; ++a)
; #pragma unroll
;             for (int b = 0; b < 2; ++b)
.LBB0_694:
	s_add_u32 s46, s24, s44
	s_addc_u32 s47, s25, s45
	s_add_u32 s48, s56, s42
	v_mov_b32_e32 v127, 0
	s_addc_u32 s49, s57, s43
	s_and_b64 vcc, exec, s[6:7]
	v_mov_b64_e32 v[0:1], 0
	v_mov_b64_e32 v[2:3], 0
	v_mov_b64_e32 v[4:5], 0
	v_mov_b64_e32 v[6:7], 0
	v_mov_b64_e32 v[8:9], 0
	v_mov_b64_e32 v[10:11], 0
	v_mov_b64_e32 v[12:13], 0
	v_mov_b64_e32 v[14:15], 0
	v_mov_b64_e32 v[16:17], 0
	v_mov_b64_e32 v[18:19], 0
	v_mov_b64_e32 v[20:21], 0
	v_mov_b64_e32 v[22:23], 0
	v_mov_b64_e32 v[24:25], 0
	v_mov_b64_e32 v[26:27], 0
	v_mov_b64_e32 v[28:29], 0
	v_mov_b64_e32 v[30:31], 0
	v_mov_b64_e32 v[32:33], 0
	v_mov_b64_e32 v[34:35], 0
	v_mov_b64_e32 v[36:37], 0
	v_mov_b64_e32 v[38:39], 0
	v_mov_b64_e32 v[40:41], 0
	v_mov_b64_e32 v[42:43], 0
	v_mov_b64_e32 v[44:45], 0
	v_mov_b64_e32 v[46:47], 0
	v_mov_b64_e32 v[48:49], 0
	v_mov_b64_e32 v[50:51], 0
	v_mov_b64_e32 v[52:53], 0
	v_mov_b64_e32 v[54:55], 0
	v_mov_b64_e32 v[56:57], 0
	v_mov_b64_e32 v[58:59], 0
	v_mov_b64_e32 v[60:61], 0
	v_mov_b64_e32 v[62:63], 0
	v_mov_b64_e32 v[64:65], 0
	v_mov_b64_e32 v[66:67], 0
	v_mov_b64_e32 v[68:69], 0
	v_mov_b64_e32 v[70:71], 0
	v_mov_b64_e32 v[72:73], 0
	v_mov_b64_e32 v[74:75], 0
	v_mov_b64_e32 v[76:77], 0
	v_mov_b64_e32 v[78:79], 0
	v_mov_b64_e32 v[80:81], 0
	v_mov_b64_e32 v[82:83], 0
	v_mov_b64_e32 v[84:85], 0
	v_mov_b64_e32 v[86:87], 0
	v_mov_b64_e32 v[88:89], 0
	v_mov_b64_e32 v[90:91], 0
	v_mov_b64_e32 v[92:93], 0
	v_mov_b64_e32 v[94:95], 0
	v_mov_b64_e32 v[96:97], 0
	v_mov_b64_e32 v[98:99], 0
	v_mov_b64_e32 v[100:101], 0
	v_mov_b64_e32 v[102:103], 0
	v_mov_b64_e32 v[104:105], 0
	v_mov_b64_e32 v[106:107], 0
	v_mov_b64_e32 v[108:109], 0
	v_mov_b64_e32 v[110:111], 0
	v_mov_b64_e32 v[112:113], 0
	v_mov_b64_e32 v[114:115], 0
	v_mov_b64_e32 v[116:117], 0
	v_mov_b64_e32 v[118:119], 0
	v_mov_b64_e32 v[120:121], 0
	v_mov_b64_e32 v[122:123], 0
	v_mov_b64_e32 v[124:125], 0
	v_mov_b64_e32 v[126:127], 0
	s_cbranch_vccnz .LBB0_697
	s_and_b64 s[54:55], s[8:9], exec
	s_cselect_b32 s73, s47, s53
	s_cselect_b32 s74, s46, s52
	s_cselect_b32 s75, s49, s51
	s_cselect_b32 s76, s48, s50
	s_add_u32 s77, s50, 0x100
	s_addc_u32 s78, s51, 0
	s_add_u32 s50, s52, 0x20080
	v_mov_b32_e32 v0, 0
	s_addc_u32 s51, s53, 0
	s_mov_b32 s52, 0
	v_mov_b64_e32 v[0:1], 0
	v_mov_b64_e32 v[2:3], 0
	v_mov_b64_e32 v[4:5], 0
	v_mov_b64_e32 v[6:7], 0
	v_mov_b64_e32 v[8:9], 0
	v_mov_b64_e32 v[10:11], 0
	v_mov_b64_e32 v[12:13], 0
	v_mov_b64_e32 v[14:15], 0
	v_mov_b64_e32 v[16:17], 0
	v_mov_b64_e32 v[18:19], 0
	v_mov_b64_e32 v[20:21], 0
	v_mov_b64_e32 v[22:23], 0
	v_mov_b64_e32 v[24:25], 0
	v_mov_b64_e32 v[26:27], 0
	v_mov_b64_e32 v[28:29], 0
	v_mov_b64_e32 v[30:31], 0
	v_mov_b64_e32 v[32:33], 0
	v_mov_b64_e32 v[34:35], 0
	v_mov_b64_e32 v[36:37], 0
	v_mov_b64_e32 v[38:39], 0
	v_mov_b64_e32 v[40:41], 0
	v_mov_b64_e32 v[42:43], 0
	v_mov_b64_e32 v[44:45], 0
	v_mov_b64_e32 v[46:47], 0
	v_mov_b64_e32 v[48:49], 0
	v_mov_b64_e32 v[50:51], 0
	v_mov_b64_e32 v[52:53], 0
	v_mov_b64_e32 v[54:55], 0
	v_mov_b64_e32 v[56:57], 0
	v_mov_b64_e32 v[58:59], 0
	v_mov_b64_e32 v[60:61], 0
	v_mov_b64_e32 v[62:63], 0
	v_mov_b64_e32 v[64:65], 0
	v_mov_b64_e32 v[66:67], 0
	v_mov_b64_e32 v[68:69], 0
	v_mov_b64_e32 v[70:71], 0
	v_mov_b64_e32 v[72:73], 0
	v_mov_b64_e32 v[74:75], 0
	v_mov_b64_e32 v[76:77], 0
	v_mov_b64_e32 v[78:79], 0
	v_mov_b64_e32 v[80:81], 0
	v_mov_b64_e32 v[82:83], 0
	v_mov_b64_e32 v[84:85], 0
	v_mov_b64_e32 v[86:87], 0
	v_mov_b64_e32 v[88:89], 0
	v_mov_b64_e32 v[90:91], 0
	v_mov_b64_e32 v[92:93], 0
	v_mov_b64_e32 v[94:95], 0
	v_mov_b64_e32 v[96:97], 0
	v_mov_b64_e32 v[98:99], 0
	v_mov_b64_e32 v[100:101], 0
	v_mov_b64_e32 v[102:103], 0
	v_mov_b64_e32 v[104:105], 0
	v_mov_b64_e32 v[106:107], 0
	v_mov_b64_e32 v[108:109], 0
	v_mov_b64_e32 v[110:111], 0
	v_mov_b64_e32 v[112:113], 0
	v_mov_b64_e32 v[114:115], 0
	v_mov_b64_e32 v[116:117], 0
	v_mov_b64_e32 v[118:119], 0
	v_mov_b64_e32 v[120:121], 0
	v_mov_b64_e32 v[122:123], 0
	v_mov_b64_e32 v[124:125], 0
	v_mov_b64_e32 v[126:127], 0

; template <class Epi, class Sched>
; __device__ __forceinline__ void gemm_phase(LAS unsigned char* lds, const Gemm g, const Sched& S, const Epi& E, const int wave_) {
;     ...
; #pragma unroll
;     for (int a = 0; a < 2; ++a)
; #pragma unroll
;         for (int b = 0; b < 2; ++b)
; #pragma unroll
;             for (int m = 0; m < 4; ++m)
; #pragma unroll
;                 for (int n = 0; n < 2; ++n) acc[a][b][m][n] = (f32x4){0.f, 0.f, 0.f, 0.f};
;     ...
;         const bool has_next = S.next(ui + 1, nxt);
;         const char* nA = has_next ? (const char*)g.A + nxt.aoff : cA; const char* nB = has_next ? (const char*)g.Bt + nxt.boff : cB;
; #pragma unroll 1
;         for (int t = 0; t < nt; t += 2) {
;             if constexpr (Epi::HOOK) { if (t == 8 || t == 16) { E.hook(acc, cur, t >> 3, wr, wc, fr, fq); PG8_WAIT_V(0); } }
;             const bool last = (t == nt - 2);
;             const char* a1 = cA + (size_t)(t + 1) * kstep;
;             const char* a2 = last ? nA : cA + (size_t)(t + 2) * kstep; const char* b2 = last ? nB : cB + (size_t)(t + 2) * kstep;
;             const char* a3 = a2 + kstep; const char* b3 = b2 + kstep;
;             PG8_LDB(B0, 0, 0); PG8_LDB(B1, 0, 1); PG8_SCHED; PG8_LDA(At, 0, 0); PG8_STAGE(PG8_SA(1, 1), a1 + hstepA, voffA);
;             PG8_WAIT_V(8); PG8_WAIT_L(0); PG8_BAR; PG8_MMA(0, 0, At, B0); PG8_MMA(0, 1, At, B1); PG8_BAR; PG8_SCHED;
;             PG8_LDA(At, 0, 1); PG8_STAGE(PG8_SB(0, 0), b2, voffB); PG8_STAGE(PG8_SB(0, 1), b2 + hstepB, voffB); PG8_STAGE(PG8_SA(0, 0), a2, voffA);
;             PG8_WAIT_V(8); PG8_WAIT_L(0); PG8_BAR; PG8_MMA(1, 0, At, B0); PG8_MMA(1, 1, At, B1); PG8_BAR; PG8_SCHED;
;             PG8_LDB(B0, 1, 0); PG8_LDB(B1, 1, 1); PG8_SCHED; PG8_LDA(At, 1, 0); PG8_STAGE(PG8_SA(0, 1), a2 + hstepA, voffA);
;             PG8_WAIT_V(8); PG8_WAIT_L(0); PG8_BAR; PG8_MMA(0, 0, At, B0); PG8_MMA(0, 1, At, B1); PG8_BAR; PG8_SCHED;
;             PG8_LDA(At, 1, 1); PG8_STAGE(PG8_SB(1, 0), b3, voffB); PG8_STAGE(PG8_SB(1, 1), b3 + hstepB, voffB); PG8_STAGE(PG8_SA(1, 0), a3, voffA);
;             PG8_WAIT_V(8); PG8_WAIT_L(0); PG8_BAR; PG8_MMA(1, 0, At, B0); PG8_MMA(1, 1, At, B1); PG8_BAR; PG8_SCHED;
;         }
;         if (wr == 0) PG8_BAR;
;         E(acc, cur, wr, wc, fr, fq);
;         if (!has_next) break;
; #pragma unroll
;         for (int a = 0; a < 2; ++a)
; #pragma unroll
;             for (int b = 0; b < 2; ++b)
.LBB0_713:
	s_add_u32 s54, s3, s50
	v_mov_b32_e32 v2, v0
	v_mov_b32_e32 v3, v0
	s_addc_u32 s55, s24, s51
	v_mov_b32_e32 v1, v0
	v_mov_b64_e32 v[136:137], v[2:3]
	v_mov_b64_e32 v[132:133], v[2:3]
	v_mov_b64_e32 v[120:121], v[2:3]
	v_mov_b64_e32 v[116:117], v[2:3]
	v_mov_b64_e32 v[104:105], v[2:3]
	v_mov_b64_e32 v[100:101], v[2:3]
	v_mov_b64_e32 v[88:89], v[2:3]
	v_mov_b64_e32 v[84:85], v[2:3]
	v_mov_b64_e32 v[128:129], v[2:3]
	v_mov_b64_e32 v[124:125], v[2:3]
	v_mov_b64_e32 v[112:113], v[2:3]
	v_mov_b64_e32 v[108:109], v[2:3]
	v_mov_b64_e32 v[96:97], v[2:3]
	v_mov_b64_e32 v[92:93], v[2:3]
	v_mov_b64_e32 v[80:81], v[2:3]
	v_mov_b64_e32 v[76:77], v[2:3]
	v_mov_b64_e32 v[72:73], v[2:3]
	v_mov_b64_e32 v[68:69], v[2:3]
	v_mov_b64_e32 v[56:57], v[2:3]
	v_mov_b64_e32 v[52:53], v[2:3]
	v_mov_b64_e32 v[40:41], v[2:3]
	v_mov_b64_e32 v[36:37], v[2:3]
	v_mov_b64_e32 v[20:21], v[2:3]
	v_mov_b64_e32 v[12:13], v[2:3]
	v_mov_b64_e32 v[64:65], v[2:3]
	v_mov_b64_e32 v[60:61], v[2:3]
	v_mov_b64_e32 v[48:49], v[2:3]
	v_mov_b64_e32 v[44:45], v[2:3]
	v_mov_b64_e32 v[32:33], v[2:3]
	v_mov_b64_e32 v[28:29], v[2:3]
	v_mov_b64_e32 v[8:9], v[2:3]
	s_add_u32 s56, s25, s52
	v_mov_b64_e32 v[134:135], v[0:1]
	v_mov_b64_e32 v[130:131], v[0:1]
	v_mov_b64_e32 v[118:119], v[0:1]
	v_mov_b64_e32 v[114:115], v[0:1]
	v_mov_b64_e32 v[102:103], v[0:1]
	v_mov_b64_e32 v[98:99], v[0:1]
	v_mov_b64_e32 v[86:87], v[0:1]
	v_mov_b64_e32 v[82:83], v[0:1]
	v_mov_b64_e32 v[126:127], v[0:1]
	v_mov_b64_e32 v[122:123], v[0:1]
	v_mov_b64_e32 v[110:111], v[0:1]
	v_mov_b64_e32 v[106:107], v[0:1]
	v_mov_b64_e32 v[94:95], v[0:1]
	v_mov_b64_e32 v[90:91], v[0:1]
	v_mov_b64_e32 v[78:79], v[0:1]
	v_mov_b64_e32 v[74:75], v[0:1]
	v_mov_b64_e32 v[70:71], v[0:1]
	v_mov_b64_e32 v[66:67], v[0:1]
	v_mov_b64_e32 v[54:55], v[0:1]
	v_mov_b64_e32 v[50:51], v[0:1]
	v_mov_b64_e32 v[38:39], v[0:1]
	v_mov_b64_e32 v[34:35], v[0:1]
	v_mov_b64_e32 v[18:19], v[0:1]
	v_mov_b64_e32 v[10:11], v[0:1]
	v_mov_b64_e32 v[62:63], v[0:1]
	v_mov_b64_e32 v[58:59], v[0:1]
	v_mov_b64_e32 v[46:47], v[0:1]
	v_mov_b64_e32 v[42:43], v[0:1]
	v_mov_b64_e32 v[30:31], v[0:1]
	v_mov_b64_e32 v[26:27], v[0:1]
	v_mov_b64_e32 v[6:7], v[0:1]
	v_mov_b64_e32 v[4:5], v[2:3]
	s_addc_u32 s57, s45, s53
	s_andn2_b64 vcc, exec, s[40:41]
	v_mov_b64_e32 v[2:3], v[0:1]
	s_cbranch_vccnz .LBB0_717
	s_and_b64 s[60:61], s[6:7], exec
	s_cselect_b32 s9, s55, s59
	s_cselect_b32 s47, s54, s58
	s_cselect_b32 s49, s57, s11
	s_cselect_b32 s81, s56, s10
	s_add_u32 s89, s10, 0x100
	s_addc_u32 s90, s11, 0
	s_add_u32 s10, s58, 0x10080
	v_mov_b32_e32 v2, 0
	s_addc_u32 s11, s59, 0
	s_mov_b32 s58, 0
	v_mov_b64_e32 v[2:3], 0
	v_mov_b64_e32 v[4:5], 0
	v_mov_b64_e32 v[6:7], 0
	v_mov_b64_e32 v[8:9], 0
	v_mov_b64_e32 v[10:11], 0
	v_mov_b64_e32 v[12:13], 0
	v_mov_b64_e32 v[14:15], 0
	v_mov_b64_e32 v[16:17], 0
	v_mov_b64_e32 v[18:19], 0
	v_mov_b64_e32 v[20:21], 0
	v_mov_b64_e32 v[22:23], 0
	v_mov_b64_e32 v[24:25], 0
	v_mov_b64_e32 v[26:27], 0
	v_mov_b64_e32 v[28:29], 0
	v_mov_b64_e32 v[30:31], 0
	v_mov_b64_e32 v[32:33], 0
	v_mov_b64_e32 v[34:35], 0
	v_mov_b64_e32 v[36:37], 0
	v_mov_b64_e32 v[38:39], 0
	v_mov_b64_e32 v[40:41], 0
	v_mov_b64_e32 v[42:43], 0
	v_mov_b64_e32 v[44:45], 0
	v_mov_b64_e32 v[46:47], 0
	v_mov_b64_e32 v[48:49], 0
	v_mov_b64_e32 v[50:51], 0
	v_mov_b64_e32 v[52:53], 0
	v_mov_b64_e32 v[54:55], 0
	v_mov_b64_e32 v[56:57], 0
	v_mov_b64_e32 v[58:59], 0
	v_mov_b64_e32 v[60:61], 0
	v_mov_b64_e32 v[62:63], 0
	v_mov_b64_e32 v[64:65], 0
	v_mov_b64_e32 v[66:67], 0
	v_mov_b64_e32 v[68:69], 0
	v_mov_b64_e32 v[70:71], 0
	v_mov_b64_e32 v[72:73], 0
	v_mov_b64_e32 v[74:75], 0
	v_mov_b64_e32 v[76:77], 0
	v_mov_b64_e32 v[78:79], 0
	v_mov_b64_e32 v[80:81], 0
	v_mov_b64_e32 v[82:83], 0
	v_mov_b64_e32 v[84:85], 0
	v_mov_b64_e32 v[86:87], 0
	v_mov_b64_e32 v[88:89], 0
	v_mov_b64_e32 v[90:91], 0
	v_mov_b64_e32 v[92:93], 0
	v_mov_b64_e32 v[94:95], 0
	v_mov_b64_e32 v[96:97], 0
	v_mov_b64_e32 v[98:99], 0
	v_mov_b64_e32 v[100:101], 0
	v_mov_b64_e32 v[102:103], 0
	v_mov_b64_e32 v[104:105], 0
	v_mov_b64_e32 v[106:107], 0
	v_mov_b64_e32 v[108:109], 0
	v_mov_b64_e32 v[110:111], 0
	v_mov_b64_e32 v[112:113], 0
	v_mov_b64_e32 v[114:115], 0
	v_mov_b64_e32 v[116:117], 0
	v_mov_b64_e32 v[118:119], 0
	v_mov_b64_e32 v[120:121], 0
	v_mov_b64_e32 v[122:123], 0
	v_mov_b64_e32 v[124:125], 0
	v_mov_b64_e32 v[126:127], 0
	v_mov_b64_e32 v[128:129], 0

; template <class Epi, class Sched>
; __device__ __forceinline__ void gemm_phase(LAS unsigned char* lds, const Gemm g, const Sched& S, const Epi& E, const int wave_) {
;     ...
; #pragma unroll
;     for (int a = 0; a < 2; ++a)
; #pragma unroll
;         for (int b = 0; b < 2; ++b)
; #pragma unroll
;             for (int m = 0; m < 4; ++m)
; #pragma unroll
;                 for (int n = 0; n < 2; ++n) acc[a][b][m][n] = (f32x4){0.f, 0.f, 0.f, 0.f};
;     ...
;         const bool has_next = S.next(ui + 1, nxt);
;         const char* nA = has_next ? (const char*)g.A + nxt.aoff : cA; const char* nB = has_next ? (const char*)g.Bt + nxt.boff : cB;
; #pragma unroll 1
;         for (int t = 0; t < nt; t += 2) {
;             if constexpr (Epi::HOOK) { if (t == 8 || t == 16) { E.hook(acc, cur, t >> 3, wr, wc, fr, fq); PG8_WAIT_V(0); } }
;             const bool last = (t == nt - 2);
;             const char* a1 = cA + (size_t)(t + 1) * kstep;
;             const char* a2 = last ? nA : cA + (size_t)(t + 2) * kstep; const char* b2 = last ? nB : cB + (size_t)(t + 2) * kstep;
;             const char* a3 = a2 + kstep; const char* b3 = b2 + kstep;
;             PG8_LDB(B0, 0, 0); PG8_LDB(B1, 0, 1); PG8_SCHED; PG8_LDA(At, 0, 0); PG8_STAGE(PG8_SA(1, 1), a1 + hstepA, voffA);
;             PG8_WAIT_V(8); PG8_WAIT_L(0); PG8_BAR; PG8_MMA(0, 0, At, B0); PG8_MMA(0, 1, At, B1); PG8_BAR; PG8_SCHED;
;             PG8_LDA(At, 0, 1); PG8_STAGE(PG8_SB(0, 0), b2, voffB); PG8_STAGE(PG8_SB(0, 1), b2 + hstepB, voffB); PG8_STAGE(PG8_SA(0, 0), a2, voffA);
;             PG8_WAIT_V(8); PG8_WAIT_L(0); PG8_BAR; PG8_MMA(1, 0, At, B0); PG8_MMA(1, 1, At, B1); PG8_BAR; PG8_SCHED;
;             PG8_LDB(B0, 1, 0); PG8_LDB(B1, 1, 1); PG8_SCHED; PG8_LDA(At, 1, 0); PG8_STAGE(PG8_SA(0, 1), a2 + hstepA, voffA);
;             PG8_WAIT_V(8); PG8_WAIT_L(0); PG8_BAR; PG8_MMA(0, 0, At, B0); PG8_MMA(0, 1, At, B1); PG8_BAR; PG8_SCHED;
;             PG8_LDA(At, 1, 1); PG8_STAGE(PG8_SB(1, 0), b3, voffB); PG8_STAGE(PG8_SB(1, 1), b3 + hstepB, voffB); PG8_STAGE(PG8_SA(1, 0), a3, voffA);
;             PG8_WAIT_V(8); PG8_WAIT_L(0); PG8_BAR; PG8_MMA(1, 0, At, B0); PG8_MMA(1, 1, At, B1); PG8_BAR; PG8_SCHED;
;         }
;         if (wr == 0) PG8_BAR;
;         E(acc, cur, wr, wc, fr, fq);
;         if (!has_next) break;
; #pragma unroll
;         for (int a = 0; a < 2; ++a)
; #pragma unroll
;             for (int b = 0; b < 2; ++b)
.LBB0_771:
	s_add_u32 s48, s28, s44
	s_addc_u32 s49, s29, s45
	s_add_u32 s50, s25, s46
	v_mov_b32_e32 v123, 0
	s_addc_u32 s51, s58, s47
	s_andn2_b64 vcc, exec, s[34:35]
	v_mov_b64_e32 v[0:1], 0
	v_mov_b64_e32 v[2:3], 0
	v_mov_b64_e32 v[4:5], 0
	v_mov_b64_e32 v[6:7], 0
	v_mov_b64_e32 v[8:9], 0
	v_mov_b64_e32 v[10:11], 0
	v_mov_b64_e32 v[12:13], 0
	v_mov_b64_e32 v[14:15], 0
	v_mov_b64_e32 v[16:17], 0
	v_mov_b64_e32 v[18:19], 0
	v_mov_b64_e32 v[20:21], 0
	v_mov_b64_e32 v[22:23], 0
	v_mov_b64_e32 v[24:25], 0
	v_mov_b64_e32 v[26:27], 0
	v_mov_b64_e32 v[28:29], 0
	v_mov_b64_e32 v[30:31], 0
	v_mov_b64_e32 v[32:33], 0
	v_mov_b64_e32 v[34:35], 0
	v_mov_b64_e32 v[36:37], 0
	v_mov_b64_e32 v[38:39], 0
	v_mov_b64_e32 v[40:41], 0
	v_mov_b64_e32 v[42:43], 0
	v_mov_b64_e32 v[44:45], 0
	v_mov_b64_e32 v[46:47], 0
	v_mov_b64_e32 v[48:49], 0
	v_mov_b64_e32 v[50:51], 0
	v_mov_b64_e32 v[52:53], 0
	v_mov_b64_e32 v[54:55], 0
	v_mov_b64_e32 v[56:57], 0
	v_mov_b64_e32 v[58:59], 0
	v_mov_b64_e32 v[60:61], 0
	v_mov_b64_e32 v[62:63], 0
	v_mov_b64_e32 v[64:65], 0
	v_mov_b64_e32 v[66:67], 0
	v_mov_b64_e32 v[68:69], 0
	v_mov_b64_e32 v[70:71], 0
	v_mov_b64_e32 v[72:73], 0
	v_mov_b64_e32 v[74:75], 0
	v_mov_b64_e32 v[76:77], 0
	v_mov_b64_e32 v[78:79], 0
	v_mov_b64_e32 v[80:81], 0
	v_mov_b64_e32 v[82:83], 0
	v_mov_b64_e32 v[84:85], 0
	v_mov_b64_e32 v[86:87], 0
	v_mov_b64_e32 v[88:89], 0
	v_mov_b64_e32 v[90:91], 0
	v_mov_b64_e32 v[92:93], 0
	v_mov_b64_e32 v[94:95], 0
	v_mov_b64_e32 v[96:97], 0
	v_mov_b64_e32 v[98:99], 0
	v_mov_b64_e32 v[100:101], 0
	v_mov_b64_e32 v[102:103], 0
	v_mov_b64_e32 v[104:105], 0
	v_mov_b64_e32 v[106:107], 0
	v_mov_b64_e32 v[108:109], 0
	v_mov_b64_e32 v[110:111], 0
	v_mov_b64_e32 v[112:113], 0
	v_mov_b64_e32 v[114:115], 0
	v_mov_b64_e32 v[116:117], 0
	v_mov_b64_e32 v[118:119], 0
	v_mov_b64_e32 v[120:121], 0
	v_mov_b64_e32 v[122:123], 0
	v_mov_b64_e32 v[124:125], 0
	v_mov_b64_e32 v[126:127], 0
	s_cbranch_vccnz .LBB0_774
	s_and_b64 s[56:57], s[6:7], exec
	s_cselect_b32 s41, s49, s55
	s_cselect_b32 s43, s48, s54
	s_cselect_b32 s75, s51, s53
	s_cselect_b32 s76, s50, s52
	s_add_u32 s77, s52, 0x100
	s_addc_u32 s78, s53, 0
	s_add_u32 s52, s54, 0x8080
	v_mov_b32_e32 v0, 0
	s_addc_u32 s53, s55, 0
	s_mov_b32 s54, 0
	v_mov_b64_e32 v[0:1], 0
	v_mov_b64_e32 v[2:3], 0
	v_mov_b64_e32 v[4:5], 0
	v_mov_b64_e32 v[6:7], 0
	v_mov_b64_e32 v[8:9], 0
	v_mov_b64_e32 v[10:11], 0
	v_mov_b64_e32 v[12:13], 0
	v_mov_b64_e32 v[14:15], 0
	v_mov_b64_e32 v[16:17], 0
	v_mov_b64_e32 v[18:19], 0
	v_mov_b64_e32 v[20:21], 0
	v_mov_b64_e32 v[22:23], 0
	v_mov_b64_e32 v[24:25], 0
	v_mov_b64_e32 v[26:27], 0
	v_mov_b64_e32 v[28:29], 0
	v_mov_b64_e32 v[30:31], 0
	v_mov_b64_e32 v[32:33], 0
	v_mov_b64_e32 v[34:35], 0
	v_mov_b64_e32 v[36:37], 0
	v_mov_b64_e32 v[38:39], 0
	v_mov_b64_e32 v[40:41], 0
	v_mov_b64_e32 v[42:43], 0
	v_mov_b64_e32 v[44:45], 0
	v_mov_b64_e32 v[46:47], 0
	v_mov_b64_e32 v[48:49], 0
	v_mov_b64_e32 v[50:51], 0
	v_mov_b64_e32 v[52:53], 0
	v_mov_b64_e32 v[54:55], 0
	v_mov_b64_e32 v[56:57], 0
	v_mov_b64_e32 v[58:59], 0
	v_mov_b64_e32 v[60:61], 0
	v_mov_b64_e32 v[62:63], 0
	v_mov_b64_e32 v[64:65], 0
	v_mov_b64_e32 v[66:67], 0
	v_mov_b64_e32 v[68:69], 0
	v_mov_b64_e32 v[70:71], 0
	v_mov_b64_e32 v[72:73], 0
	v_mov_b64_e32 v[74:75], 0
	v_mov_b64_e32 v[76:77], 0
	v_mov_b64_e32 v[78:79], 0
	v_mov_b64_e32 v[80:81], 0
	v_mov_b64_e32 v[82:83], 0
	v_mov_b64_e32 v[84:85], 0
	v_mov_b64_e32 v[86:87], 0
	v_mov_b64_e32 v[88:89], 0
	v_mov_b64_e32 v[90:91], 0
	v_mov_b64_e32 v[92:93], 0
	v_mov_b64_e32 v[94:95], 0
	v_mov_b64_e32 v[96:97], 0
	v_mov_b64_e32 v[98:99], 0
	v_mov_b64_e32 v[100:101], 0
	v_mov_b64_e32 v[102:103], 0
	v_mov_b64_e32 v[104:105], 0
	v_mov_b64_e32 v[106:107], 0
	v_mov_b64_e32 v[108:109], 0
	v_mov_b64_e32 v[110:111], 0
	v_mov_b64_e32 v[112:113], 0
	v_mov_b64_e32 v[114:115], 0
	v_mov_b64_e32 v[116:117], 0
	v_mov_b64_e32 v[118:119], 0
	v_mov_b64_e32 v[120:121], 0
	v_mov_b64_e32 v[122:123], 0
	v_mov_b64_e32 v[124:125], 0
	v_mov_b64_e32 v[126:127], 0

; #define PG8_BAR __builtin_amdgcn_s_barrier()
; template <class Epi, class Sched>
; __device__ __forceinline__ void gemm_phase(LAS unsigned char* lds, const Gemm g, const Sched& S, const Epi& E, const int wave_) {
;     ...
;         const bool has_next = S.next(ui + 1, nxt);
;         const char* nA = has_next ? (const char*)g.A + nxt.aoff : cA; const char* nB = has_next ? (const char*)g.Bt + nxt.boff : cB;
; #pragma unroll 1
;         for (int t = 0; t < nt; t += 2) {
;             if constexpr (Epi::HOOK) { if (t == 8 || t == 16) { E.hook(acc, cur, t >> 3, wr, wc, fr, fq); PG8_WAIT_V(0); } }
;             const bool last = (t == nt - 2);
;             const char* a1 = cA + (size_t)(t + 1) * kstep;
;             const char* a2 = last ? nA : cA + (size_t)(t + 2) * kstep; const char* b2 = last ? nB : cB + (size_t)(t + 2) * kstep;
;             const char* a3 = a2 + kstep; const char* b3 = b2 + kstep;
;             PG8_LDB(B0, 0, 0); PG8_LDB(B1, 0, 1); PG8_SCHED; PG8_LDA(At, 0, 0); PG8_STAGE(PG8_SA(1, 1), a1 + hstepA, voffA);
;             PG8_WAIT_V(8); PG8_WAIT_L(0); PG8_BAR; PG8_MMA(0, 0, At, B0); PG8_MMA(0, 1, At, B1); PG8_BAR; PG8_SCHED;
;             PG8_LDA(At, 0, 1); PG8_STAGE(PG8_SB(0, 0), b2, voffB); PG8_STAGE(PG8_SB(0, 1), b2 + hstepB, voffB); PG8_STAGE(PG8_SA(0, 0), a2, voffA);
;             PG8_WAIT_V(8); PG8_WAIT_L(0); PG8_BAR; PG8_MMA(1, 0, At, B0); PG8_MMA(1, 1, At, B1); PG8_BAR; PG8_SCHED;
;             PG8_LDB(B0, 1, 0); PG8_LDB(B1, 1, 1); PG8_SCHED; PG8_LDA(At, 1, 0); PG8_STAGE(PG8_SA(0, 1), a2 + hstepA, voffA);
;             PG8_WAIT_V(8); PG8_WAIT_L(0); PG8_BAR; PG8_MMA(0, 0, At, B0); PG8_MMA(0, 1, At, B1); PG8_BAR; PG8_SCHED;
;             PG8_LDA(At, 1, 1); PG8_STAGE(PG8_SB(1, 0), b3, voffB); PG8_STAGE(PG8_SB(1, 1), b3 + hstepB, voffB); PG8_STAGE(PG8_SA(1, 0), a3, voffA);
;             PG8_WAIT_V(8); PG8_WAIT_L(0); PG8_BAR; PG8_MMA(1, 0, At, B0); PG8_MMA(1, 1, At, B1); PG8_BAR; PG8_SCHED;
;         }
;         if (wr == 0) PG8_BAR;
;         E(acc, cur, wr, wc, fr, fq);
;         if (!has_next) break;
; #pragma unroll
;         for (int a = 0; a < 2; ++a)
; #pragma unroll
;             for (int b = 0; b < 2; ++b)
; #pragma unroll
;                 for (int m = 0; m < 4; ++m)
; #pragma unroll
;                     for (int n = 0; n < 2; ++n) acc[a][b][m][n] = (f32x4){0.f, 0.f, 0.f, 0.f};
;         cur = nxt; cA = nA; cB = nB; ++ui;
.LBB0_796:
	s_add_u32 s48, s25, s44
	s_addc_u32 s49, s58, s45
	s_add_u32 s50, s28, s46
	v_mov_b32_e32 v123, 0
	s_addc_u32 s51, s29, s47
	s_andn2_b64 vcc, exec, s[34:35]
	v_mov_b64_e32 v[0:1], 0
	v_mov_b64_e32 v[2:3], 0
	v_mov_b64_e32 v[4:5], 0
	v_mov_b64_e32 v[6:7], 0
	v_mov_b64_e32 v[8:9], 0
	v_mov_b64_e32 v[10:11], 0
	v_mov_b64_e32 v[12:13], 0
	v_mov_b64_e32 v[14:15], 0
	v_mov_b64_e32 v[16:17], 0
	v_mov_b64_e32 v[18:19], 0
	v_mov_b64_e32 v[20:21], 0
	v_mov_b64_e32 v[22:23], 0
	v_mov_b64_e32 v[24:25], 0
	v_mov_b64_e32 v[26:27], 0
	v_mov_b64_e32 v[28:29], 0
	v_mov_b64_e32 v[30:31], 0
	v_mov_b64_e32 v[32:33], 0
	v_mov_b64_e32 v[34:35], 0
	v_mov_b64_e32 v[36:37], 0
	v_mov_b64_e32 v[38:39], 0
	v_mov_b64_e32 v[40:41], 0
	v_mov_b64_e32 v[42:43], 0
	v_mov_b64_e32 v[44:45], 0
	v_mov_b64_e32 v[46:47], 0
	v_mov_b64_e32 v[48:49], 0
	v_mov_b64_e32 v[50:51], 0
	v_mov_b64_e32 v[52:53], 0
	v_mov_b64_e32 v[54:55], 0
	v_mov_b64_e32 v[56:57], 0
	v_mov_b64_e32 v[58:59], 0
	v_mov_b64_e32 v[60:61], 0
	v_mov_b64_e32 v[62:63], 0
	v_mov_b64_e32 v[64:65], 0
	v_mov_b64_e32 v[66:67], 0
	v_mov_b64_e32 v[68:69], 0
	v_mov_b64_e32 v[70:71], 0
	v_mov_b64_e32 v[72:73], 0
	v_mov_b64_e32 v[74:75], 0
	v_mov_b64_e32 v[76:77], 0
	v_mov_b64_e32 v[78:79], 0
	v_mov_b64_e32 v[80:81], 0
	v_mov_b64_e32 v[82:83], 0
	v_mov_b64_e32 v[84:85], 0
	v_mov_b64_e32 v[86:87], 0
	v_mov_b64_e32 v[88:89], 0
	v_mov_b64_e32 v[90:91], 0
	v_mov_b64_e32 v[92:93], 0
	v_mov_b64_e32 v[94:95], 0
	v_mov_b64_e32 v[96:97], 0
	v_mov_b64_e32 v[98:99], 0
	v_mov_b64_e32 v[100:101], 0
	v_mov_b64_e32 v[102:103], 0
	v_mov_b64_e32 v[104:105], 0
	v_mov_b64_e32 v[106:107], 0
	v_mov_b64_e32 v[108:109], 0
	v_mov_b64_e32 v[110:111], 0
	v_mov_b64_e32 v[112:113], 0
	v_mov_b64_e32 v[114:115], 0
	v_mov_b64_e32 v[116:117], 0
	v_mov_b64_e32 v[118:119], 0
	v_mov_b64_e32 v[120:121], 0
	v_mov_b64_e32 v[122:123], 0
	v_mov_b64_e32 v[124:125], 0
	v_mov_b64_e32 v[126:127], 0
	s_cbranch_vccnz .LBB0_799
	s_and_b64 s[56:57], s[6:7], exec
	s_cselect_b32 s41, s49, s55
	s_cselect_b32 s43, s48, s54
	s_cselect_b32 s72, s51, s53
	s_cselect_b32 s73, s50, s52
	s_add_u32 s74, s52, 0x100
	s_addc_u32 s75, s53, 0
	s_add_u32 s52, s54, 0x8080
	v_mov_b32_e32 v0, 0
	s_addc_u32 s53, s55, 0
	s_mov_b32 s54, 0
	v_mov_b64_e32 v[0:1], 0
	v_mov_b64_e32 v[2:3], 0
	v_mov_b64_e32 v[4:5], 0
	v_mov_b64_e32 v[6:7], 0
	v_mov_b64_e32 v[8:9], 0
	v_mov_b64_e32 v[10:11], 0
	v_mov_b64_e32 v[12:13], 0
	v_mov_b64_e32 v[14:15], 0
	v_mov_b64_e32 v[16:17], 0
	v_mov_b64_e32 v[18:19], 0
	v_mov_b64_e32 v[20:21], 0
	v_mov_b64_e32 v[22:23], 0
	v_mov_b64_e32 v[24:25], 0
	v_mov_b64_e32 v[26:27], 0
	v_mov_b64_e32 v[28:29], 0
	v_mov_b64_e32 v[30:31], 0
	v_mov_b64_e32 v[32:33], 0
	v_mov_b64_e32 v[34:35], 0
	v_mov_b64_e32 v[36:37], 0
	v_mov_b64_e32 v[38:39], 0
	v_mov_b64_e32 v[40:41], 0
	v_mov_b64_e32 v[42:43], 0
	v_mov_b64_e32 v[44:45], 0
	v_mov_b64_e32 v[46:47], 0
	v_mov_b64_e32 v[48:49], 0
	v_mov_b64_e32 v[50:51], 0
	v_mov_b64_e32 v[52:53], 0
	v_mov_b64_e32 v[54:55], 0
	v_mov_b64_e32 v[56:57], 0
	v_mov_b64_e32 v[58:59], 0
	v_mov_b64_e32 v[60:61], 0
	v_mov_b64_e32 v[62:63], 0
	v_mov_b64_e32 v[64:65], 0
	v_mov_b64_e32 v[66:67], 0
	v_mov_b64_e32 v[68:69], 0
	v_mov_b64_e32 v[70:71], 0
	v_mov_b64_e32 v[72:73], 0
	v_mov_b64_e32 v[74:75], 0
	v_mov_b64_e32 v[76:77], 0
	v_mov_b64_e32 v[78:79], 0
	v_mov_b64_e32 v[80:81], 0
	v_mov_b64_e32 v[82:83], 0
	v_mov_b64_e32 v[84:85], 0
	v_mov_b64_e32 v[86:87], 0
	v_mov_b64_e32 v[88:89], 0
	v_mov_b64_e32 v[90:91], 0
	v_mov_b64_e32 v[92:93], 0
	v_mov_b64_e32 v[94:95], 0
	v_mov_b64_e32 v[96:97], 0
	v_mov_b64_e32 v[98:99], 0
	v_mov_b64_e32 v[100:101], 0
	v_mov_b64_e32 v[102:103], 0
	v_mov_b64_e32 v[104:105], 0
	v_mov_b64_e32 v[106:107], 0
	v_mov_b64_e32 v[108:109], 0
	v_mov_b64_e32 v[110:111], 0
	v_mov_b64_e32 v[112:113], 0
	v_mov_b64_e32 v[114:115], 0
	v_mov_b64_e32 v[116:117], 0
	v_mov_b64_e32 v[118:119], 0
	v_mov_b64_e32 v[120:121], 0
	v_mov_b64_e32 v[122:123], 0
	v_mov_b64_e32 v[124:125], 0
	v_mov_b64_e32 v[126:127], 0

; #define PG8_BAR __builtin_amdgcn_s_barrier()
; template <class Epi, class Sched>
; __device__ __forceinline__ void gemm_phase(LAS unsigned char* lds, const Gemm g, const Sched& S, const Epi& E, const int wave_) {
;     ...
;         const bool has_next = S.next(ui + 1, nxt);
;         const char* nA = has_next ? (const char*)g.A + nxt.aoff : cA; const char* nB = has_next ? (const char*)g.Bt + nxt.boff : cB;
; #pragma unroll 1
;         for (int t = 0; t < nt; t += 2) {
;             if constexpr (Epi::HOOK) { if (t == 8 || t == 16) { E.hook(acc, cur, t >> 3, wr, wc, fr, fq); PG8_WAIT_V(0); } }
;             const bool last = (t == nt - 2);
;             const char* a1 = cA + (size_t)(t + 1) * kstep;
;             const char* a2 = last ? nA : cA + (size_t)(t + 2) * kstep; const char* b2 = last ? nB : cB + (size_t)(t + 2) * kstep;
;             const char* a3 = a2 + kstep; const char* b3 = b2 + kstep;
;             PG8_LDB(B0, 0, 0); PG8_LDB(B1, 0, 1); PG8_SCHED; PG8_LDA(At, 0, 0); PG8_STAGE(PG8_SA(1, 1), a1 + hstepA, voffA);
;             PG8_WAIT_V(8); PG8_WAIT_L(0); PG8_BAR; PG8_MMA(0, 0, At, B0); PG8_MMA(0, 1, At, B1); PG8_BAR; PG8_SCHED;
;             PG8_LDA(At, 0, 1); PG8_STAGE(PG8_SB(0, 0), b2, voffB); PG8_STAGE(PG8_SB(0, 1), b2 + hstepB, voffB); PG8_STAGE(PG8_SA(0, 0), a2, voffA);
;             PG8_WAIT_V(8); PG8_WAIT_L(0); PG8_BAR; PG8_MMA(1, 0, At, B0); PG8_MMA(1, 1, At, B1); PG8_BAR; PG8_SCHED;
;             PG8_LDB(B0, 1, 0); PG8_LDB(B1, 1, 1); PG8_SCHED; PG8_LDA(At, 1, 0); PG8_STAGE(PG8_SA(0, 1), a2 + hstepA, voffA);
;             PG8_WAIT_V(8); PG8_WAIT_L(0); PG8_BAR; PG8_MMA(0, 0, At, B0); PG8_MMA(0, 1, At, B1); PG8_BAR; PG8_SCHED;
;             PG8_LDA(At, 1, 1); PG8_STAGE(PG8_SB(1, 0), b3, voffB); PG8_STAGE(PG8_SB(1, 1), b3 + hstepB, voffB); PG8_STAGE(PG8_SA(1, 0), a3, voffA);
;             PG8_WAIT_V(8); PG8_WAIT_L(0); PG8_BAR; PG8_MMA(1, 0, At, B0); PG8_MMA(1, 1, At, B1); PG8_BAR; PG8_SCHED;
;         }
;         if (wr == 0) PG8_BAR;
;         E(acc, cur, wr, wc, fr, fq);
;         if (!has_next) break;
; #pragma unroll
;         for (int a = 0; a < 2; ++a)
; #pragma unroll
;             for (int b = 0; b < 2; ++b)
; #pragma unroll
;                 for (int m = 0; m < 4; ++m)
; #pragma unroll
;                     for (int n = 0; n < 2; ++n) acc[a][b][m][n] = (f32x4){0.f, 0.f, 0.f, 0.f};
;         cur = nxt; cA = nA; cB = nB; ++ui;
.LBB0_946:
	s_add_u32 s46, s6, s42
	s_addc_u32 s47, s7, s43
	s_add_u32 s48, s24, s44
	v_mov_b32_e32 v123, 0
	s_addc_u32 s49, s25, s45
	s_andn2_b64 vcc, exec, s[34:35]
	v_mov_b64_e32 v[0:1], 0
	v_mov_b64_e32 v[2:3], 0
	v_mov_b64_e32 v[4:5], 0
	v_mov_b64_e32 v[6:7], 0
	v_mov_b64_e32 v[8:9], 0
	v_mov_b64_e32 v[10:11], 0
	v_mov_b64_e32 v[12:13], 0
	v_mov_b64_e32 v[14:15], 0
	v_mov_b64_e32 v[16:17], 0
	v_mov_b64_e32 v[18:19], 0
	v_mov_b64_e32 v[20:21], 0
	v_mov_b64_e32 v[22:23], 0
	v_mov_b64_e32 v[24:25], 0
	v_mov_b64_e32 v[26:27], 0
	v_mov_b64_e32 v[28:29], 0
	v_mov_b64_e32 v[30:31], 0
	v_mov_b64_e32 v[32:33], 0
	v_mov_b64_e32 v[34:35], 0
	v_mov_b64_e32 v[36:37], 0
	v_mov_b64_e32 v[38:39], 0
	v_mov_b64_e32 v[40:41], 0
	v_mov_b64_e32 v[42:43], 0
	v_mov_b64_e32 v[44:45], 0
	v_mov_b64_e32 v[46:47], 0
	v_mov_b64_e32 v[48:49], 0
	v_mov_b64_e32 v[50:51], 0
	v_mov_b64_e32 v[52:53], 0
	v_mov_b64_e32 v[54:55], 0
	v_mov_b64_e32 v[56:57], 0
	v_mov_b64_e32 v[58:59], 0
	v_mov_b64_e32 v[60:61], 0
	v_mov_b64_e32 v[62:63], 0
	v_mov_b64_e32 v[64:65], 0
	v_mov_b64_e32 v[66:67], 0
	v_mov_b64_e32 v[68:69], 0
	v_mov_b64_e32 v[70:71], 0
	v_mov_b64_e32 v[72:73], 0
	v_mov_b64_e32 v[74:75], 0
	v_mov_b64_e32 v[76:77], 0
	v_mov_b64_e32 v[78:79], 0
	v_mov_b64_e32 v[80:81], 0
	v_mov_b64_e32 v[82:83], 0
	v_mov_b64_e32 v[84:85], 0
	v_mov_b64_e32 v[86:87], 0
	v_mov_b64_e32 v[88:89], 0
	v_mov_b64_e32 v[90:91], 0
	v_mov_b64_e32 v[92:93], 0
	v_mov_b64_e32 v[94:95], 0
	v_mov_b64_e32 v[96:97], 0
	v_mov_b64_e32 v[98:99], 0
	v_mov_b64_e32 v[100:101], 0
	v_mov_b64_e32 v[102:103], 0
	v_mov_b64_e32 v[104:105], 0
	v_mov_b64_e32 v[106:107], 0
	v_mov_b64_e32 v[108:109], 0
	v_mov_b64_e32 v[110:111], 0
	v_mov_b64_e32 v[112:113], 0
	v_mov_b64_e32 v[114:115], 0
	v_mov_b64_e32 v[116:117], 0
	v_mov_b64_e32 v[118:119], 0
	v_mov_b64_e32 v[120:121], 0
	v_mov_b64_e32 v[122:123], 0
	v_mov_b64_e32 v[124:125], 0
	v_mov_b64_e32 v[126:127], 0
	s_cbranch_vccnz .LBB0_949
	s_and_b64 s[56:57], s[4:5], exec
	s_cselect_b32 s39, s47, s55
	s_cselect_b32 s41, s46, s54
	s_cselect_b32 s73, s49, s53
	s_cselect_b32 s74, s48, s52
	s_add_u32 s75, s52, 0x100
	s_addc_u32 s76, s53, 0
	s_add_u32 s52, s54, 0x20080
	v_mov_b32_e32 v0, 0
	s_addc_u32 s53, s55, 0
	s_mov_b32 s54, 0
	v_mov_b64_e32 v[0:1], 0
	v_mov_b64_e32 v[2:3], 0
	v_mov_b64_e32 v[4:5], 0
	v_mov_b64_e32 v[6:7], 0
	v_mov_b64_e32 v[8:9], 0
	v_mov_b64_e32 v[10:11], 0
	v_mov_b64_e32 v[12:13], 0
	v_mov_b64_e32 v[14:15], 0
	v_mov_b64_e32 v[16:17], 0
	v_mov_b64_e32 v[18:19], 0
	v_mov_b64_e32 v[20:21], 0
	v_mov_b64_e32 v[22:23], 0
	v_mov_b64_e32 v[24:25], 0
	v_mov_b64_e32 v[26:27], 0
	v_mov_b64_e32 v[28:29], 0
	v_mov_b64_e32 v[30:31], 0
	v_mov_b64_e32 v[32:33], 0
	v_mov_b64_e32 v[34:35], 0
	v_mov_b64_e32 v[36:37], 0
	v_mov_b64_e32 v[38:39], 0
	v_mov_b64_e32 v[40:41], 0
	v_mov_b64_e32 v[42:43], 0
	v_mov_b64_e32 v[44:45], 0
	v_mov_b64_e32 v[46:47], 0
	v_mov_b64_e32 v[48:49], 0
	v_mov_b64_e32 v[50:51], 0
	v_mov_b64_e32 v[52:53], 0
	v_mov_b64_e32 v[54:55], 0
	v_mov_b64_e32 v[56:57], 0
	v_mov_b64_e32 v[58:59], 0
	v_mov_b64_e32 v[60:61], 0
	v_mov_b64_e32 v[62:63], 0
	v_mov_b64_e32 v[64:65], 0
	v_mov_b64_e32 v[66:67], 0
	v_mov_b64_e32 v[68:69], 0
	v_mov_b64_e32 v[70:71], 0
	v_mov_b64_e32 v[72:73], 0
	v_mov_b64_e32 v[74:75], 0
	v_mov_b64_e32 v[76:77], 0
	v_mov_b64_e32 v[78:79], 0
	v_mov_b64_e32 v[80:81], 0
	v_mov_b64_e32 v[82:83], 0
	v_mov_b64_e32 v[84:85], 0
	v_mov_b64_e32 v[86:87], 0
	v_mov_b64_e32 v[88:89], 0
	v_mov_b64_e32 v[90:91], 0
	v_mov_b64_e32 v[92:93], 0
	v_mov_b64_e32 v[94:95], 0
	v_mov_b64_e32 v[96:97], 0
	v_mov_b64_e32 v[98:99], 0
	v_mov_b64_e32 v[100:101], 0
	v_mov_b64_e32 v[102:103], 0
	v_mov_b64_e32 v[104:105], 0
	v_mov_b64_e32 v[106:107], 0
	v_mov_b64_e32 v[108:109], 0
	v_mov_b64_e32 v[110:111], 0
	v_mov_b64_e32 v[112:113], 0
	v_mov_b64_e32 v[114:115], 0
	v_mov_b64_e32 v[116:117], 0
	v_mov_b64_e32 v[118:119], 0
	v_mov_b64_e32 v[120:121], 0
	v_mov_b64_e32 v[122:123], 0
	v_mov_b64_e32 v[124:125], 0
	v_mov_b64_e32 v[126:127], 0

; #define PG8_BAR __builtin_amdgcn_s_barrier()
; template <class Epi, class Sched>
; __device__ __forceinline__ void gemm_phase(LAS unsigned char* lds, const Gemm g, const Sched& S, const Epi& E, const int wave_) {
;     ...
;         const bool has_next = S.next(ui + 1, nxt);
;         const char* nA = has_next ? (const char*)g.A + nxt.aoff : cA; const char* nB = has_next ? (const char*)g.Bt + nxt.boff : cB;
; #pragma unroll 1
;         for (int t = 0; t < nt; t += 2) {
;             if constexpr (Epi::HOOK) { if (t == 8 || t == 16) { E.hook(acc, cur, t >> 3, wr, wc, fr, fq); PG8_WAIT_V(0); } }
;             const bool last = (t == nt - 2);
;             const char* a1 = cA + (size_t)(t + 1) * kstep;
;             const char* a2 = last ? nA : cA + (size_t)(t + 2) * kstep; const char* b2 = last ? nB : cB + (size_t)(t + 2) * kstep;
;             const char* a3 = a2 + kstep; const char* b3 = b2 + kstep;
;             PG8_LDB(B0, 0, 0); PG8_LDB(B1, 0, 1); PG8_SCHED; PG8_LDA(At, 0, 0); PG8_STAGE(PG8_SA(1, 1), a1 + hstepA, voffA);
;             PG8_WAIT_V(8); PG8_WAIT_L(0); PG8_BAR; PG8_MMA(0, 0, At, B0); PG8_MMA(0, 1, At, B1); PG8_BAR; PG8_SCHED;
;             PG8_LDA(At, 0, 1); PG8_STAGE(PG8_SB(0, 0), b2, voffB); PG8_STAGE(PG8_SB(0, 1), b2 + hstepB, voffB); PG8_STAGE(PG8_SA(0, 0), a2, voffA);
;             PG8_WAIT_V(8); PG8_WAIT_L(0); PG8_BAR; PG8_MMA(1, 0, At, B0); PG8_MMA(1, 1, At, B1); PG8_BAR; PG8_SCHED;
;             PG8_LDB(B0, 1, 0); PG8_LDB(B1, 1, 1); PG8_SCHED; PG8_LDA(At, 1, 0); PG8_STAGE(PG8_SA(0, 1), a2 + hstepA, voffA);
;             PG8_WAIT_V(8); PG8_WAIT_L(0); PG8_BAR; PG8_MMA(0, 0, At, B0); PG8_MMA(0, 1, At, B1); PG8_BAR; PG8_SCHED;
;             PG8_LDA(At, 1, 1); PG8_STAGE(PG8_SB(1, 0), b3, voffB); PG8_STAGE(PG8_SB(1, 1), b3 + hstepB, voffB); PG8_STAGE(PG8_SA(1, 0), a3, voffA);
;             PG8_WAIT_V(8); PG8_WAIT_L(0); PG8_BAR; PG8_MMA(1, 0, At, B0); PG8_MMA(1, 1, At, B1); PG8_BAR; PG8_SCHED;
;         }
;         if (wr == 0) PG8_BAR;
;         E(acc, cur, wr, wc, fr, fq);
;         if (!has_next) break;
; #pragma unroll
;         for (int a = 0; a < 2; ++a)
; #pragma unroll
;             for (int b = 0; b < 2; ++b)
; #pragma unroll
;                 for (int m = 0; m < 4; ++m)
; #pragma unroll
;                     for (int n = 0; n < 2; ++n) acc[a][b][m][n] = (f32x4){0.f, 0.f, 0.f, 0.f};
;         cur = nxt; cA = nA; cB = nB; ++ui;
.LBB0_1023:
	s_add_u32 s46, s8, s42
	s_addc_u32 s47, s9, s43
	s_add_u32 s48, s24, s44
	v_mov_b32_e32 v123, 0
	s_addc_u32 s49, s25, s45
	s_andn2_b64 vcc, exec, s[34:35]
	v_mov_b64_e32 v[0:1], 0
	v_mov_b64_e32 v[2:3], 0
	v_mov_b64_e32 v[4:5], 0
	v_mov_b64_e32 v[6:7], 0
	v_mov_b64_e32 v[8:9], 0
	v_mov_b64_e32 v[10:11], 0
	v_mov_b64_e32 v[12:13], 0
	v_mov_b64_e32 v[14:15], 0
	v_mov_b64_e32 v[16:17], 0
	v_mov_b64_e32 v[18:19], 0
	v_mov_b64_e32 v[20:21], 0
	v_mov_b64_e32 v[22:23], 0
	v_mov_b64_e32 v[24:25], 0
	v_mov_b64_e32 v[26:27], 0
	v_mov_b64_e32 v[28:29], 0
	v_mov_b64_e32 v[30:31], 0
	v_mov_b64_e32 v[32:33], 0
	v_mov_b64_e32 v[34:35], 0
	v_mov_b64_e32 v[36:37], 0
	v_mov_b64_e32 v[38:39], 0
	v_mov_b64_e32 v[40:41], 0
	v_mov_b64_e32 v[42:43], 0
	v_mov_b64_e32 v[44:45], 0
	v_mov_b64_e32 v[46:47], 0
	v_mov_b64_e32 v[48:49], 0
	v_mov_b64_e32 v[50:51], 0
	v_mov_b64_e32 v[52:53], 0
	v_mov_b64_e32 v[54:55], 0
	v_mov_b64_e32 v[56:57], 0
	v_mov_b64_e32 v[58:59], 0
	v_mov_b64_e32 v[60:61], 0
	v_mov_b64_e32 v[62:63], 0
	v_mov_b64_e32 v[64:65], 0
	v_mov_b64_e32 v[66:67], 0
	v_mov_b64_e32 v[68:69], 0
	v_mov_b64_e32 v[70:71], 0
	v_mov_b64_e32 v[72:73], 0
	v_mov_b64_e32 v[74:75], 0
	v_mov_b64_e32 v[76:77], 0
	v_mov_b64_e32 v[78:79], 0
	v_mov_b64_e32 v[80:81], 0
	v_mov_b64_e32 v[82:83], 0
	v_mov_b64_e32 v[84:85], 0
	v_mov_b64_e32 v[86:87], 0
	v_mov_b64_e32 v[88:89], 0
	v_mov_b64_e32 v[90:91], 0
	v_mov_b64_e32 v[92:93], 0
	v_mov_b64_e32 v[94:95], 0
	v_mov_b64_e32 v[96:97], 0
	v_mov_b64_e32 v[98:99], 0
	v_mov_b64_e32 v[100:101], 0
	v_mov_b64_e32 v[102:103], 0
	v_mov_b64_e32 v[104:105], 0
	v_mov_b64_e32 v[106:107], 0
	v_mov_b64_e32 v[108:109], 0
	v_mov_b64_e32 v[110:111], 0
	v_mov_b64_e32 v[112:113], 0
	v_mov_b64_e32 v[114:115], 0
	v_mov_b64_e32 v[116:117], 0
	v_mov_b64_e32 v[118:119], 0
	v_mov_b64_e32 v[120:121], 0
	v_mov_b64_e32 v[122:123], 0
	v_mov_b64_e32 v[124:125], 0
	v_mov_b64_e32 v[126:127], 0
	s_cbranch_vccnz .LBB0_1032
	s_and_b64 s[54:55], s[4:5], exec
	s_cselect_b32 s89, s47, s51
	s_cselect_b32 s90, s46, s50
	s_cselect_b32 s91, s49, s53
	s_cselect_b32 s92, s48, s52
	s_lshl_b32 s54, s88, 8
	s_ashr_i32 s55, s54, 31
	s_add_u32 s93, s52, 0x100
	s_addc_u32 s94, s53, 0
	s_lshl_b64 s[52:53], s[54:55], 1
	v_lshl_add_u32 v2, s87, 8, v191
	v_mov_b64_e32 v[0:1], s[52:53]
	v_mad_i64_i32 v[0:1], s[52:53], v2, s70, v[0:1]
	v_lshl_add_u64 v[182:183], v[176:177], 0, v[0:1]
	v_mov_b32_e32 v0, 0
	s_mov_b32 s56, 0
	v_mov_b64_e32 v[0:1], 0
	v_mov_b64_e32 v[2:3], 0
	v_mov_b64_e32 v[4:5], 0
	v_mov_b64_e32 v[6:7], 0
	v_mov_b64_e32 v[8:9], 0
	v_mov_b64_e32 v[10:11], 0
	v_mov_b64_e32 v[12:13], 0
	v_mov_b64_e32 v[14:15], 0
	v_mov_b64_e32 v[16:17], 0
	v_mov_b64_e32 v[18:19], 0
	v_mov_b64_e32 v[20:21], 0
	v_mov_b64_e32 v[22:23], 0
	v_mov_b64_e32 v[24:25], 0
	v_mov_b64_e32 v[26:27], 0
	v_mov_b64_e32 v[28:29], 0
	v_mov_b64_e32 v[30:31], 0
	v_mov_b64_e32 v[32:33], 0
	v_mov_b64_e32 v[34:35], 0
	v_mov_b64_e32 v[36:37], 0
	v_mov_b64_e32 v[38:39], 0
	v_mov_b64_e32 v[40:41], 0
	v_mov_b64_e32 v[42:43], 0
	v_mov_b64_e32 v[44:45], 0
	v_mov_b64_e32 v[46:47], 0
	v_mov_b64_e32 v[48:49], 0
	v_mov_b64_e32 v[50:51], 0
	v_mov_b64_e32 v[52:53], 0
	v_mov_b64_e32 v[54:55], 0
	v_mov_b64_e32 v[56:57], 0
	v_mov_b64_e32 v[58:59], 0
	v_mov_b64_e32 v[60:61], 0
	v_mov_b64_e32 v[62:63], 0
	v_mov_b64_e32 v[64:65], 0
	v_mov_b64_e32 v[66:67], 0
	v_mov_b64_e32 v[68:69], 0
	v_mov_b64_e32 v[70:71], 0
	v_mov_b64_e32 v[72:73], 0
	v_mov_b64_e32 v[74:75], 0
	v_mov_b64_e32 v[76:77], 0
	v_mov_b64_e32 v[78:79], 0
	v_mov_b64_e32 v[80:81], 0
	v_mov_b64_e32 v[82:83], 0
	v_mov_b64_e32 v[84:85], 0
	v_mov_b64_e32 v[86:87], 0
	v_mov_b64_e32 v[88:89], 0
	v_mov_b64_e32 v[90:91], 0
	v_mov_b64_e32 v[92:93], 0
	v_mov_b64_e32 v[94:95], 0
	v_mov_b64_e32 v[96:97], 0
	v_mov_b64_e32 v[98:99], 0
	v_mov_b64_e32 v[100:101], 0
	v_mov_b64_e32 v[102:103], 0
	v_mov_b64_e32 v[104:105], 0
	v_mov_b64_e32 v[106:107], 0
	v_mov_b64_e32 v[108:109], 0
	v_mov_b64_e32 v[110:111], 0
	v_mov_b64_e32 v[112:113], 0
	v_mov_b64_e32 v[114:115], 0
	v_mov_b64_e32 v[116:117], 0
	v_mov_b64_e32 v[118:119], 0
	v_mov_b64_e32 v[120:121], 0
	v_mov_b64_e32 v[122:123], 0
	v_mov_b64_e32 v[124:125], 0
	v_mov_b64_e32 v[126:127], 0
	s_cmp_lt_i32 s56, 16
	s_cbranch_scc0 .LBB0_1031

; #define PG8_BAR __builtin_amdgcn_s_barrier()
; template <class Epi, class Sched>
; __device__ __forceinline__ void gemm_phase(LAS unsigned char* lds, const Gemm g, const Sched& S, const Epi& E, const int wave_) {
;     ...
;         const bool has_next = S.next(ui + 1, nxt);
;         const char* nA = has_next ? (const char*)g.A + nxt.aoff : cA; const char* nB = has_next ? (const char*)g.Bt + nxt.boff : cB;
; #pragma unroll 1
;         for (int t = 0; t < nt; t += 2) {
;             if constexpr (Epi::HOOK) { if (t == 8 || t == 16) { E.hook(acc, cur, t >> 3, wr, wc, fr, fq); PG8_WAIT_V(0); } }
;             const bool last = (t == nt - 2);
;             const char* a1 = cA + (size_t)(t + 1) * kstep;
;             const char* a2 = last ? nA : cA + (size_t)(t + 2) * kstep; const char* b2 = last ? nB : cB + (size_t)(t + 2) * kstep;
;             const char* a3 = a2 + kstep; const char* b3 = b2 + kstep;
;             PG8_LDB(B0, 0, 0); PG8_LDB(B1, 0, 1); PG8_SCHED; PG8_LDA(At, 0, 0); PG8_STAGE(PG8_SA(1, 1), a1 + hstepA, voffA);
;             PG8_WAIT_V(8); PG8_WAIT_L(0); PG8_BAR; PG8_MMA(0, 0, At, B0); PG8_MMA(0, 1, At, B1); PG8_BAR; PG8_SCHED;
;             PG8_LDA(At, 0, 1); PG8_STAGE(PG8_SB(0, 0), b2, voffB); PG8_STAGE(PG8_SB(0, 1), b2 + hstepB, voffB); PG8_STAGE(PG8_SA(0, 0), a2, voffA);
;             PG8_WAIT_V(8); PG8_WAIT_L(0); PG8_BAR; PG8_MMA(1, 0, At, B0); PG8_MMA(1, 1, At, B1); PG8_BAR; PG8_SCHED;
;             PG8_LDB(B0, 1, 0); PG8_LDB(B1, 1, 1); PG8_SCHED; PG8_LDA(At, 1, 0); PG8_STAGE(PG8_SA(0, 1), a2 + hstepA, voffA);
;             PG8_WAIT_V(8); PG8_WAIT_L(0); PG8_BAR; PG8_MMA(0, 0, At, B0); PG8_MMA(0, 1, At, B1); PG8_BAR; PG8_SCHED;
;             PG8_LDA(At, 1, 1); PG8_STAGE(PG8_SB(1, 0), b3, voffB); PG8_STAGE(PG8_SB(1, 1), b3 + hstepB, voffB); PG8_STAGE(PG8_SA(1, 0), a3, voffA);
;             PG8_WAIT_V(8); PG8_WAIT_L(0); PG8_BAR; PG8_MMA(1, 0, At, B0); PG8_MMA(1, 1, At, B1); PG8_BAR; PG8_SCHED;
;         }
;         if (wr == 0) PG8_BAR;
;         E(acc, cur, wr, wc, fr, fq);
;         if (!has_next) break;
; #pragma unroll
;         for (int a = 0; a < 2; ++a)
; #pragma unroll
;             for (int b = 0; b < 2; ++b)
; #pragma unroll
;                 for (int m = 0; m < 4; ++m)
; #pragma unroll
;                     for (int n = 0; n < 2; ++n) acc[a][b][m][n] = (f32x4){0.f, 0.f, 0.f, 0.f};
;         cur = nxt; cA = nA; cB = nB; ++ui;
.LBB0_1107:
	s_add_u32 s44, s24, s40
	s_addc_u32 s45, s25, s41
	s_add_u32 s46, s54, s42
	v_mov_b32_e32 v123, 0
	s_addc_u32 s47, s55, s43
	s_andn2_b64 vcc, exec, s[28:29]
	v_mov_b64_e32 v[0:1], 0
	v_mov_b64_e32 v[2:3], 0
	v_mov_b64_e32 v[4:5], 0
	v_mov_b64_e32 v[6:7], 0
	v_mov_b64_e32 v[8:9], 0
	v_mov_b64_e32 v[10:11], 0
	v_mov_b64_e32 v[12:13], 0
	v_mov_b64_e32 v[14:15], 0
	v_mov_b64_e32 v[16:17], 0
	v_mov_b64_e32 v[18:19], 0
	v_mov_b64_e32 v[20:21], 0
	v_mov_b64_e32 v[22:23], 0
	v_mov_b64_e32 v[24:25], 0
	v_mov_b64_e32 v[26:27], 0
	v_mov_b64_e32 v[28:29], 0
	v_mov_b64_e32 v[30:31], 0
	v_mov_b64_e32 v[32:33], 0
	v_mov_b64_e32 v[34:35], 0
	v_mov_b64_e32 v[36:37], 0
	v_mov_b64_e32 v[38:39], 0
	v_mov_b64_e32 v[40:41], 0
	v_mov_b64_e32 v[42:43], 0
	v_mov_b64_e32 v[44:45], 0
	v_mov_b64_e32 v[46:47], 0
	v_mov_b64_e32 v[48:49], 0
	v_mov_b64_e32 v[50:51], 0
	v_mov_b64_e32 v[52:53], 0
	v_mov_b64_e32 v[54:55], 0
	v_mov_b64_e32 v[56:57], 0
	v_mov_b64_e32 v[58:59], 0
	v_mov_b64_e32 v[60:61], 0
	v_mov_b64_e32 v[62:63], 0
	v_mov_b64_e32 v[64:65], 0
	v_mov_b64_e32 v[66:67], 0
	v_mov_b64_e32 v[68:69], 0
	v_mov_b64_e32 v[70:71], 0
	v_mov_b64_e32 v[72:73], 0
	v_mov_b64_e32 v[74:75], 0
	v_mov_b64_e32 v[76:77], 0
	v_mov_b64_e32 v[78:79], 0
	v_mov_b64_e32 v[80:81], 0
	v_mov_b64_e32 v[82:83], 0
	v_mov_b64_e32 v[84:85], 0
	v_mov_b64_e32 v[86:87], 0
	v_mov_b64_e32 v[88:89], 0
	v_mov_b64_e32 v[90:91], 0
	v_mov_b64_e32 v[92:93], 0
	v_mov_b64_e32 v[94:95], 0
	v_mov_b64_e32 v[96:97], 0
	v_mov_b64_e32 v[98:99], 0
	v_mov_b64_e32 v[100:101], 0
	v_mov_b64_e32 v[102:103], 0
	v_mov_b64_e32 v[104:105], 0
	v_mov_b64_e32 v[106:107], 0
	v_mov_b64_e32 v[108:109], 0
	v_mov_b64_e32 v[110:111], 0
	v_mov_b64_e32 v[112:113], 0
	v_mov_b64_e32 v[114:115], 0
	v_mov_b64_e32 v[116:117], 0
	v_mov_b64_e32 v[118:119], 0
	v_mov_b64_e32 v[120:121], 0
	v_mov_b64_e32 v[122:123], 0
	v_mov_b64_e32 v[124:125], 0
	v_mov_b64_e32 v[126:127], 0
	s_cbranch_vccnz .LBB0_1110
	s_and_b64 s[52:53], s[4:5], exec
	s_cselect_b32 s37, s45, s51
	s_cselect_b32 s39, s44, s50
	s_cselect_b32 s68, s47, s49
	s_cselect_b32 s69, s46, s48
	s_add_u32 s70, s48, 0x100
	s_addc_u32 s71, s49, 0
	s_add_u32 s48, s50, 0x40080
	v_mov_b32_e32 v0, 0
	s_addc_u32 s49, s51, 0
	s_mov_b32 s50, 0
	v_mov_b64_e32 v[0:1], 0
	v_mov_b64_e32 v[2:3], 0
	v_mov_b64_e32 v[4:5], 0
	v_mov_b64_e32 v[6:7], 0
	v_mov_b64_e32 v[8:9], 0
	v_mov_b64_e32 v[10:11], 0
	v_mov_b64_e32 v[12:13], 0
	v_mov_b64_e32 v[14:15], 0
	v_mov_b64_e32 v[16:17], 0
	v_mov_b64_e32 v[18:19], 0
	v_mov_b64_e32 v[20:21], 0
	v_mov_b64_e32 v[22:23], 0
	v_mov_b64_e32 v[24:25], 0
	v_mov_b64_e32 v[26:27], 0
	v_mov_b64_e32 v[28:29], 0
	v_mov_b64_e32 v[30:31], 0
	v_mov_b64_e32 v[32:33], 0
	v_mov_b64_e32 v[34:35], 0
	v_mov_b64_e32 v[36:37], 0
	v_mov_b64_e32 v[38:39], 0
	v_mov_b64_e32 v[40:41], 0
	v_mov_b64_e32 v[42:43], 0
	v_mov_b64_e32 v[44:45], 0
	v_mov_b64_e32 v[46:47], 0
	v_mov_b64_e32 v[48:49], 0
	v_mov_b64_e32 v[50:51], 0
	v_mov_b64_e32 v[52:53], 0
	v_mov_b64_e32 v[54:55], 0
	v_mov_b64_e32 v[56:57], 0
	v_mov_b64_e32 v[58:59], 0
	v_mov_b64_e32 v[60:61], 0
	v_mov_b64_e32 v[62:63], 0
	v_mov_b64_e32 v[64:65], 0
	v_mov_b64_e32 v[66:67], 0
	v_mov_b64_e32 v[68:69], 0
	v_mov_b64_e32 v[70:71], 0
	v_mov_b64_e32 v[72:73], 0
	v_mov_b64_e32 v[74:75], 0
	v_mov_b64_e32 v[76:77], 0
	v_mov_b64_e32 v[78:79], 0
	v_mov_b64_e32 v[80:81], 0
	v_mov_b64_e32 v[82:83], 0
	v_mov_b64_e32 v[84:85], 0
	v_mov_b64_e32 v[86:87], 0
	v_mov_b64_e32 v[88:89], 0
	v_mov_b64_e32 v[90:91], 0
	v_mov_b64_e32 v[92:93], 0
	v_mov_b64_e32 v[94:95], 0
	v_mov_b64_e32 v[96:97], 0
	v_mov_b64_e32 v[98:99], 0
	v_mov_b64_e32 v[100:101], 0
	v_mov_b64_e32 v[102:103], 0
	v_mov_b64_e32 v[104:105], 0
	v_mov_b64_e32 v[106:107], 0
	v_mov_b64_e32 v[108:109], 0
	v_mov_b64_e32 v[110:111], 0
	v_mov_b64_e32 v[112:113], 0
	v_mov_b64_e32 v[114:115], 0
	v_mov_b64_e32 v[116:117], 0
	v_mov_b64_e32 v[118:119], 0
	v_mov_b64_e32 v[120:121], 0
	v_mov_b64_e32 v[122:123], 0
	v_mov_b64_e32 v[124:125], 0
	v_mov_b64_e32 v[126:127], 0

; #define PG8_BAR __builtin_amdgcn_s_barrier()
; template <class Epi, class Sched>
; __device__ __forceinline__ void gemm_phase(LAS unsigned char* lds, const Gemm g, const Sched& S, const Epi& E, const int wave_) {
;     ...
;         const bool has_next = S.next(ui + 1, nxt);
;         const char* nA = has_next ? (const char*)g.A + nxt.aoff : cA; const char* nB = has_next ? (const char*)g.Bt + nxt.boff : cB;
; #pragma unroll 1
;         for (int t = 0; t < nt; t += 2) {
;             if constexpr (Epi::HOOK) { if (t == 8 || t == 16) { E.hook(acc, cur, t >> 3, wr, wc, fr, fq); PG8_WAIT_V(0); } }
;             const bool last = (t == nt - 2);
;             const char* a1 = cA + (size_t)(t + 1) * kstep;
;             const char* a2 = last ? nA : cA + (size_t)(t + 2) * kstep; const char* b2 = last ? nB : cB + (size_t)(t + 2) * kstep;
;             const char* a3 = a2 + kstep; const char* b3 = b2 + kstep;
;             PG8_LDB(B0, 0, 0); PG8_LDB(B1, 0, 1); PG8_SCHED; PG8_LDA(At, 0, 0); PG8_STAGE(PG8_SA(1, 1), a1 + hstepA, voffA);
;             PG8_WAIT_V(8); PG8_WAIT_L(0); PG8_BAR; PG8_MMA(0, 0, At, B0); PG8_MMA(0, 1, At, B1); PG8_BAR; PG8_SCHED;
;             PG8_LDA(At, 0, 1); PG8_STAGE(PG8_SB(0, 0), b2, voffB); PG8_STAGE(PG8_SB(0, 1), b2 + hstepB, voffB); PG8_STAGE(PG8_SA(0, 0), a2, voffA);
;             PG8_WAIT_V(8); PG8_WAIT_L(0); PG8_BAR; PG8_MMA(1, 0, At, B0); PG8_MMA(1, 1, At, B1); PG8_BAR; PG8_SCHED;
;             PG8_LDB(B0, 1, 0); PG8_LDB(B1, 1, 1); PG8_SCHED; PG8_LDA(At, 1, 0); PG8_STAGE(PG8_SA(0, 1), a2 + hstepA, voffA);
;             PG8_WAIT_V(8); PG8_WAIT_L(0); PG8_BAR; PG8_MMA(0, 0, At, B0); PG8_MMA(0, 1, At, B1); PG8_BAR; PG8_SCHED;
;             PG8_LDA(At, 1, 1); PG8_STAGE(PG8_SB(1, 0), b3, voffB); PG8_STAGE(PG8_SB(1, 1), b3 + hstepB, voffB); PG8_STAGE(PG8_SA(1, 0), a3, voffA);
;             PG8_WAIT_V(8); PG8_WAIT_L(0); PG8_BAR; PG8_MMA(1, 0, At, B0); PG8_MMA(1, 1, At, B1); PG8_BAR; PG8_SCHED;
;         }
;         if (wr == 0) PG8_BAR;
;         E(acc, cur, wr, wc, fr, fq);
;         if (!has_next) break;
; #pragma unroll
;         for (int a = 0; a < 2; ++a)
; #pragma unroll
;             for (int b = 0; b < 2; ++b)
; #pragma unroll
;                 for (int m = 0; m < 4; ++m)
; #pragma unroll
;                     for (int n = 0; n < 2; ++n) acc[a][b][m][n] = (f32x4){0.f, 0.f, 0.f, 0.f};
;         cur = nxt; cA = nA; cB = nB; ++ui;
.LBB0_1178:
	s_andn2_b64 vcc, exec, s[42:43]
	s_add_u32 s30, s3, s18
	s_addc_u32 s31, s44, s19
	v_cndmask_b32_e64 v0, 0, 1, s[42:43]
	s_add_u32 s34, s45, s28
	v_mov_b32_e32 v127, 0
	v_cmp_ne_u32_e64 s[8:9], 1, v0
	s_addc_u32 s35, s46, s29
	s_and_b64 vcc, exec, s[6:7]
	v_mov_b64_e32 v[6:7], 0
	v_mov_b64_e32 v[8:9], 0
	v_mov_b64_e32 v[10:11], 0
	v_mov_b64_e32 v[12:13], 0
	v_mov_b64_e32 v[14:15], 0
	v_mov_b64_e32 v[16:17], 0
	v_mov_b64_e32 v[18:19], 0
	v_mov_b64_e32 v[20:21], 0
	v_mov_b64_e32 v[22:23], 0
	v_mov_b64_e32 v[24:25], 0
	v_mov_b64_e32 v[26:27], 0
	v_mov_b64_e32 v[28:29], 0
	v_mov_b64_e32 v[30:31], 0
	v_mov_b64_e32 v[32:33], 0
	v_mov_b64_e32 v[34:35], 0
	v_mov_b64_e32 v[36:37], 0
	v_mov_b64_e32 v[38:39], 0
	v_mov_b64_e32 v[40:41], 0
	v_mov_b64_e32 v[42:43], 0
	v_mov_b64_e32 v[44:45], 0
	v_mov_b64_e32 v[46:47], 0
	v_mov_b64_e32 v[48:49], 0
	v_mov_b64_e32 v[50:51], 0
	v_mov_b64_e32 v[52:53], 0
	v_mov_b64_e32 v[54:55], 0
	v_mov_b64_e32 v[56:57], 0
	v_mov_b64_e32 v[58:59], 0
	v_mov_b64_e32 v[60:61], 0
	v_mov_b64_e32 v[62:63], 0
	v_mov_b64_e32 v[64:65], 0
	v_mov_b64_e32 v[66:67], 0
	v_mov_b64_e32 v[68:69], 0
	v_mov_b64_e32 v[70:71], 0
	v_mov_b64_e32 v[72:73], 0
	v_mov_b64_e32 v[74:75], 0
	v_mov_b64_e32 v[76:77], 0
	v_mov_b64_e32 v[78:79], 0
	v_mov_b64_e32 v[80:81], 0
	v_mov_b64_e32 v[82:83], 0
	v_mov_b64_e32 v[84:85], 0
	v_mov_b64_e32 v[86:87], 0
	v_mov_b64_e32 v[88:89], 0
	v_mov_b64_e32 v[90:91], 0
	v_mov_b64_e32 v[92:93], 0
	v_mov_b64_e32 v[94:95], 0
	v_mov_b64_e32 v[96:97], 0
	v_mov_b64_e32 v[98:99], 0
	v_mov_b64_e32 v[100:101], 0
	v_mov_b64_e32 v[102:103], 0
	v_mov_b64_e32 v[104:105], 0
	v_mov_b64_e32 v[106:107], 0
	v_mov_b64_e32 v[108:109], 0
	v_mov_b64_e32 v[110:111], 0
	v_mov_b64_e32 v[112:113], 0
	v_mov_b64_e32 v[114:115], 0
	v_mov_b64_e32 v[116:117], 0
	v_mov_b64_e32 v[118:119], 0
	v_mov_b64_e32 v[120:121], 0
	v_mov_b64_e32 v[122:123], 0
	v_mov_b64_e32 v[124:125], 0
	v_mov_b64_e32 v[126:127], 0
	s_waitcnt lgkmcnt(0)
	v_mov_b32_e32 v5, v127
	v_mov_b32_e32 v4, v127
	v_mov_b32_e32 v3, v127
	v_mov_b32_e32 v2, v127
	v_mov_b32_e32 v1, v127
	v_mov_b32_e32 v0, v127
	s_cbranch_vccnz .LBB0_1181
	s_and_b64 s[42:43], s[42:43], exec
	s_cselect_b32 s37, s31, s41
	s_cselect_b32 s59, s30, s40
	s_cselect_b32 s60, s35, s39
	s_cselect_b32 s61, s34, s38
	s_add_u32 s62, s38, 0x100
	s_addc_u32 s63, s39, 0
	s_add_u32 s38, s40, 0x40080
	v_mov_b32_e32 v0, 0
	s_addc_u32 s39, s41, 0
	s_mov_b32 s40, 0
	v_mov_b64_e32 v[0:1], 0
	v_mov_b64_e32 v[2:3], 0
	v_mov_b64_e32 v[4:5], 0
	v_mov_b64_e32 v[6:7], 0
	v_mov_b64_e32 v[8:9], 0
	v_mov_b64_e32 v[10:11], 0
	v_mov_b64_e32 v[12:13], 0
	v_mov_b64_e32 v[14:15], 0
	v_mov_b64_e32 v[16:17], 0
	v_mov_b64_e32 v[18:19], 0
	v_mov_b64_e32 v[20:21], 0
	v_mov_b64_e32 v[22:23], 0
	v_mov_b64_e32 v[24:25], 0
	v_mov_b64_e32 v[26:27], 0
	v_mov_b64_e32 v[28:29], 0
	v_mov_b64_e32 v[30:31], 0
	v_mov_b64_e32 v[32:33], 0
	v_mov_b64_e32 v[34:35], 0
	v_mov_b64_e32 v[36:37], 0
	v_mov_b64_e32 v[38:39], 0
	v_mov_b64_e32 v[40:41], 0
	v_mov_b64_e32 v[42:43], 0
	v_mov_b64_e32 v[44:45], 0
	v_mov_b64_e32 v[46:47], 0
	v_mov_b64_e32 v[48:49], 0
	v_mov_b64_e32 v[50:51], 0
	v_mov_b64_e32 v[52:53], 0
	v_mov_b64_e32 v[54:55], 0
	v_mov_b64_e32 v[56:57], 0
	v_mov_b64_e32 v[58:59], 0
	v_mov_b64_e32 v[60:61], 0
	v_mov_b64_e32 v[62:63], 0
	v_mov_b64_e32 v[64:65], 0
	v_mov_b64_e32 v[66:67], 0
	v_mov_b64_e32 v[68:69], 0
	v_mov_b64_e32 v[70:71], 0
	v_mov_b64_e32 v[72:73], 0
	v_mov_b64_e32 v[74:75], 0
	v_mov_b64_e32 v[76:77], 0
	v_mov_b64_e32 v[78:79], 0
	v_mov_b64_e32 v[80:81], 0
	v_mov_b64_e32 v[82:83], 0
	v_mov_b64_e32 v[84:85], 0
	v_mov_b64_e32 v[86:87], 0
	v_mov_b64_e32 v[88:89], 0
	v_mov_b64_e32 v[90:91], 0
	v_mov_b64_e32 v[92:93], 0
	v_mov_b64_e32 v[94:95], 0
	v_mov_b64_e32 v[96:97], 0
	v_mov_b64_e32 v[98:99], 0
	v_mov_b64_e32 v[100:101], 0
	v_mov_b64_e32 v[102:103], 0
	v_mov_b64_e32 v[104:105], 0
	v_mov_b64_e32 v[106:107], 0
	v_mov_b64_e32 v[108:109], 0
	v_mov_b64_e32 v[110:111], 0
	v_mov_b64_e32 v[112:113], 0
	v_mov_b64_e32 v[114:115], 0
	v_mov_b64_e32 v[116:117], 0
	v_mov_b64_e32 v[118:119], 0
	v_mov_b64_e32 v[120:121], 0
	v_mov_b64_e32 v[122:123], 0
	v_mov_b64_e32 v[124:125], 0
	v_mov_b64_e32 v[126:127], 0
